# attention phase rewritten by hand: K/V gathered by coalesced LDS-DMA into per-wave LDS ring
# speedup vs baseline: 1.2371x; 1.2371x over previous
; template <class T> __device__ __forceinline__ T launder(T p) { asm volatile("" : "+s"(p)); return p; }
; __device__ __forceinline__ int otid() { int t = threadIdx.x; asm volatile("" : "+v"(t)); return t; }
; __device__ __forceinline__ void phase_attn(KP kp, int l, unsigned char* shm) {
;   kp = launder(kp);
;   const int tid = otid(), lane = tid & 63, w = __builtin_amdgcn_readfirstlane(tid >> 6);
;   unsigned char* ws = kp->ws;
;   unsigned char* tileb = shm + w * 5120;
;   unsigned short* selw = (unsigned short*)(shm + w * 5120 + 4608);
;   const unsigned tr_addr = (unsigned)(size_t)tileb + (unsigned)((4 * (lane >> 4) + ((lane & 15) >> 2)) * 144 + (lane & 3) * 8);
;   bf16_t* Q = (bf16_t*)(ws + W_Q);
;   const unsigned short* SEL = (const unsigned short*)(ws + W_SEL);
;   const int nn = lane & 15, kg = lane >> 4;
;   const int ks8 = lane >> 3, dc = lane & 7;
;   for (int q = blockIdx.x * 8 + w; q < MT; q += gridDim.x * 8) {
;     int r = q;
;     if (gridDim.x == 256 && q < MP) r = ((q >> 3) & 7) * 4096 + (q >> 11) * 256 + ((q >> 6) & 31) * 8 + (q & 7);
;     const bf16_t *kbase, *vbase;
;     int n;
;     if (r < MP) {
;       const int b = r >> 12, t = r & 4095;
;       kbase = (const bf16_t*)(ws + W_KP) + (size_t)b * 4096 * 128;
;       vbase = (const bf16_t*)(ws + W_VP) + (size_t)b * 4096 * 128;
;       n = ((t >> 6) + 1) * 64;
;     } else {
;       const int sb = (r - MP) >> 5;
;       kbase = (const bf16_t*)(ws + W_KS) + (size_t)(l * 16 + sb) * 2080 * 128;
;       vbase = (const bf16_t*)(ws + W_VS) + (size_t)(l * 16 + sb) * 2080 * 128;
;       n = 2080;
;     }
;     const int cnt = n < 256 ? n : 256;
;     {
;       u32x2 sv = *(const u32x2*)(SEL + (size_t)r * 256 + lane * 4);
;       const int k0 = lane * 4;
;       unsigned a0 = sv[0] & 0xffffu, a1 = sv[0] >> 16, a2 = sv[1] & 0xffffu, a3 = sv[1] >> 16;
;       a0 = (k0 < cnt) ? a0 : 0u; a1 = (k0 + 1 < cnt) ? a1 : 0u; a2 = (k0 + 2 < cnt) ? a2 : 0u; a3 = (k0 + 3 < cnt) ? a3 : 0u;
;       u32x2 o;
;       o[0] = a0 | (a1 << 16); o[1] = a2 | (a3 << 16);
;       *(u32x2*)(selw + lane * 4) = o;
;     }
;     ...
;       if (nn < 4) {
;         const bf16_t* qp = Q + (size_t)r * 512 + (kvh * 4 + nn) * 64 + kg * 8;
;         bq0 = *(const bf16x8*)qp;
;         bq1 = *(const bf16x8*)(qp + 32);
;       }
.LBB0_3447:
	s_or_b64 exec, exec, s[0:1]
	v_readlane_b32 s0, v254, 2
	v_readlane_b32 s1, v254, 3
	s_waitcnt lgkmcnt(0)
	s_barrier
	v_readlane_b32 s2, v254, 15
	v_readlane_b32 s4, v255, 8
	v_readlane_b32 s3, v255, 24
	v_readlane_b32 s5, v254, 51
	v_readfirstlane_b32 s6, v244
	s_load_dwordx2 s[0:1], s[0:1], 0xb0
	s_lshr_b32 s6, s6, 6
	s_add_i32 s2, s2, s6
	s_cmp_lt_i32 s2, 0x8200
	s_cbranch_scc0 .LBB0_3464
	s_mul_i32 s46, s6, 0x4400
	s_add_i32 s47, s46, 0x1000
	s_add_i32 s48, s46, 0x2000
	s_add_i32 s49, s46, 0x3000
	s_add_i32 s52, s46, 0x4000
	v_and_b32_e32 v211, 15, v252
	v_lshrrev_b32_e32 v212, 4, v252
	v_and_b32_e32 v213, 7, v252
	v_lshlrev_b32_e32 v197, 1, v212
	v_xor_b32_e32 v197, v197, v213
	v_lshlrev_b32_e32 v197, 4, v197
	v_add_u32_e32 v193, 0x1000, v197
	v_add_u32_e32 v194, 0xc00, v197
	v_add_u32_e32 v195, 0x800, v197
	v_add_u32_e32 v196, 0x400, v197
	v_bfe_u32 v213, v211, 1, 2
	v_lshlrev_b32_e32 v213, 1, v213
	v_xor_b32_e32 v213, v213, v212
	v_lshlrev_b32_e32 v213, 4, v213
	v_lshl_add_u32 v213, v211, 7, v213
	v_add_u32_e32 v180, s46, v213
	v_xor_b32_e32 v181, 64, v180
	v_lshrrev_b32_e32 v214, 2, v211
	v_lshl_add_u32 v214, v212, 2, v214
	v_bfe_u32 v215, v214, 1, 2
	v_bfe_u32 v216, v211, 1, 1
	v_and_b32_e32 v217, 1, v211
	v_lshlrev_b32_e32 v217, 3, v217
	v_lshl_add_u32 v218, v214, 7, v217
	v_lshl_add_u32 v218, v216, 4, v218
	v_add_u32_e32 v218, s46, v218
	v_xor_b32_e32 v197, 0, v215
	v_lshl_add_u32 v182, v197, 5, v218
	v_xor_b32_e32 v197, 1, v215
	v_lshl_add_u32 v183, v197, 5, v218
	v_xor_b32_e32 v197, 2, v215
	v_lshl_add_u32 v184, v197, 5, v218
	v_xor_b32_e32 v197, 3, v215
	v_lshl_add_u32 v185, v197, 5, v218
	v_lshlrev_b32_e32 v188, 3, v252
	v_add_u32_e32 v186, s52, v188
	v_lshrrev_b32_e32 v197, 3, v252
	v_lshl_add_u32 v187, v197, 1, s52
	v_lshlrev_b32_e32 v189, 7, v211
	v_lshl_add_u32 v189, v212, 4, v189
	v_lshlrev_b32_e32 v190, 7, v211
	v_lshl_add_u32 v190, v212, 3, v190
	v_xor_b32_e32 v197, 16, v252
	v_lshlrev_b32_e32 v191, 2, v197
	v_xor_b32_e32 v197, 32, v252
	v_lshlrev_b32_e32 v192, 2, v197
	v_cmp_gt_u32_e64 s[42:43], 4, v211
	v_mov_b32_e32 v144, 0
	v_mov_b32_e32 v145, 0
	v_mov_b32_e32 v146, 0
	v_mov_b32_e32 v147, 0
	v_mov_b32_e32 v148, 0
	v_mov_b32_e32 v149, 0
	v_mov_b32_e32 v150, 0
	v_mov_b32_e32 v151, 0
	v_mov_b32_e32 v152, 0
	v_mov_b32_e32 v153, 0
	v_mov_b32_e32 v154, 0
	v_mov_b32_e32 v155, 0
	v_mov_b32_e32 v156, 0
	v_mov_b32_e32 v157, 0
	v_mov_b32_e32 v158, 0
	v_mov_b32_e32 v159, 0
	s_waitcnt lgkmcnt(0)
	s_mov_b32 s51, s2
	s_cmp_lg_u32 s5, 0
	s_cbranch_scc1 .Lattn_noswz_1
	s_cmp_ge_i32 s2, 0x8000
	s_cbranch_scc1 .Lattn_noswz_1
	s_lshl_b32 s6, s2, 9
	s_and_b32 s6, s6, 0x7000
	s_lshr_b32 s7, s2, 3
	s_and_b32 s8, s7, 0xffffff00
	s_and_b32 s7, s7, 0xf8
	s_or_b32 s6, s6, s8
	s_or_b32 s6, s6, s7
	s_and_b32 s7, s2, 7
	s_or_b32 s51, s6, s7
.Lattn_noswz_1:
	s_cmp_ge_i32 s51, 0x8000
	s_cbranch_scc1 .Lattn_samp_2
	s_lshr_b32 s6, s51, 12
	s_lshl_b32 s6, s6, 20
	s_add_u32 s7, s6, 0x9b3f000
	s_add_u32 s8, s6, 0xa33f000
	s_bfe_u32 s9, s51, 0x60006
	s_add_i32 s9, s9, 1
	s_min_u32 s9, s9, 4
	s_lshl_b32 s45, s9, 6
	s_branch .Lattn_join_3
.Lattn_samp_2:
	s_sub_i32 s6, s51, 0x8000
	s_lshr_b32 s6, s6, 5
	s_add_i32 s6, s6, s3
	s_mul_i32 s6, s6, 0x82000
	s_add_u32 s7, s6, 0x18b21000
	s_add_u32 s8, s6, 0x19b61000
	s_movk_i32 s45, 0x100
.Lattn_join_3:
	s_add_u32 s28, s0, s7
	s_addc_u32 s29, s1, 0
	s_add_u32 s30, s0, s8
	s_addc_u32 s31, s1, 0
	s_lshl_b32 s6, s51, 9
	s_add_u32 s6, s6, 0x1b3c2000
	s_add_u32 s38, s0, s6
	s_addc_u32 s39, s1, 0
	s_lshl_b32 s6, s51, 10
	s_add_u32 s7, s6, 0x7ac0000
	s_add_u32 s40, s0, s7
	s_addc_u32 s41, s1, 0
	s_add_u32 s7, s6, 0x1c402000
	s_add_u32 s36, s0, s7
	s_addc_u32 s37, s1, 0
	global_load_dwordx2 v[198:199], v188, s[38:39]
	s_mov_b64 exec, s[42:43]
	global_load_dwordx4 v[144:147], v189, s[40:41]
	global_load_dwordx4 v[148:151], v189, s[40:41] offset:64
	global_load_dwordx4 v[152:155], v189, s[40:41] offset:512
	global_load_dwordx4 v[156:159], v189, s[40:41] offset:576
	s_mov_b64 exec, -1
	s_waitcnt vmcnt(0)
	s_lshr_b32 s6, s45, 2
	v_cmp_gt_u32_e32 vcc, s6, v252
	s_nop 1
	v_cndmask_b32_e32 v198, 0, v198, vcc
	v_cndmask_b32_e32 v199, 0, v199, vcc
	ds_write_b64 v186, v[198:199]
	ds_read_u16 v0, v187 offset:0
	ds_read_u16 v1, v187 offset:16
	ds_read_u16 v2, v187 offset:32
	ds_read_u16 v3, v187 offset:48
	ds_read_u16 v4, v187 offset:64
	ds_read_u16 v5, v187 offset:80
	ds_read_u16 v6, v187 offset:96
	ds_read_u16 v7, v187 offset:112
	s_waitcnt lgkmcnt(0)
	v_lshl_add_u32 v0, v0, 8, v193
	v_lshl_add_u32 v1, v1, 8, v194
	v_lshl_add_u32 v2, v2, 8, v195
	v_lshl_add_u32 v3, v3, 8, v196
	v_lshl_add_u32 v4, v4, 8, v193
	v_lshl_add_u32 v5, v5, 8, v194
	v_lshl_add_u32 v6, v6, 8, v195
	v_lshl_add_u32 v7, v7, 8, v196
	ds_read_u16 v8, v187 offset:128
	ds_read_u16 v9, v187 offset:144
	ds_read_u16 v10, v187 offset:160
	ds_read_u16 v11, v187 offset:176
	ds_read_u16 v12, v187 offset:192
	ds_read_u16 v13, v187 offset:208
	ds_read_u16 v14, v187 offset:224
	ds_read_u16 v15, v187 offset:240
	s_waitcnt lgkmcnt(0)
	v_lshl_add_u32 v8, v8, 8, v193
	v_lshl_add_u32 v9, v9, 8, v194
	v_lshl_add_u32 v10, v10, 8, v195
	v_lshl_add_u32 v11, v11, 8, v196
	v_lshl_add_u32 v12, v12, 8, v193
	v_lshl_add_u32 v13, v13, 8, v194
	v_lshl_add_u32 v14, v14, 8, v195
	v_lshl_add_u32 v15, v15, 8, v196
	ds_read_u16 v16, v187 offset:256
	ds_read_u16 v18, v187 offset:272
	ds_read_u16 v19, v187 offset:288
	ds_read_u16 v20, v187 offset:304
	ds_read_u16 v21, v187 offset:320
	ds_read_u16 v22, v187 offset:336
	ds_read_u16 v23, v187 offset:352
	ds_read_u16 v24, v187 offset:368
	s_waitcnt lgkmcnt(0)
; __device__ __forceinline__ void phase_attn(KP kp, int l, unsigned char* shm) {
;     ...
;         for (int hb = 0; hb < 2; ++hb) {
;           bf16x8 ka[8][2];
;           if (kvh == 1 && hb == 0) {
; #pragma unroll
;             for (int k8 = 0; k8 < 8; ++k8) { ka[k8][0] = kpre[k8][0]; ka[k8][1] = kpre[k8][1]; }
;           } else {
; #pragma unroll
;             for (int k8 = 0; k8 < 8; ++k8) {
;               const int idx = selw[(hb * 8 + k8) * 16 + nn];
;               const bf16_t* kp = kbase + (size_t)idx * 128 + kvh * 64 + kg * 8;
;               ka[k8][0] = *(const bf16x8*)kp;
;               ka[k8][1] = *(const bf16x8*)(kp + 32);
;             }
;           }
;           __builtin_amdgcn_sched_barrier(0);
; #pragma unroll
;           for (int k8 = 0; k8 < 8; ++k8) {
;             f32x4 a = (f32x4){0.f, 0.f, 0.f, 0.f};
;             a = __builtin_amdgcn_mfma_f32_16x16x32_bf16(ka[k8][0], bq0, a, 0, 0, 0);
;             a = __builtin_amdgcn_mfma_f32_16x16x32_bf16(ka[k8][1], bq1, a, 0, 0, 0);
;             lg[hb * 8 + k8] = a;
;           }
;           __builtin_amdgcn_sched_barrier(0);
	v_lshl_add_u32 v16, v16, 8, v193
	v_lshl_add_u32 v18, v18, 8, v194
	v_lshl_add_u32 v19, v19, 8, v195
	v_lshl_add_u32 v20, v20, 8, v196
	v_lshl_add_u32 v21, v21, 8, v193
	v_lshl_add_u32 v22, v22, 8, v194
	v_lshl_add_u32 v23, v23, 8, v195
	v_lshl_add_u32 v24, v24, 8, v196
	ds_read_u16 v25, v187 offset:384
	ds_read_u16 v26, v187 offset:400
	ds_read_u16 v27, v187 offset:416
	ds_read_u16 v28, v187 offset:432
	ds_read_u16 v29, v187 offset:448
	ds_read_u16 v30, v187 offset:464
	ds_read_u16 v31, v187 offset:480
	ds_read_u16 v219, v187 offset:496
	s_waitcnt lgkmcnt(0)
	v_lshl_add_u32 v25, v25, 8, v193
	v_lshl_add_u32 v26, v26, 8, v194
	v_lshl_add_u32 v27, v27, 8, v195
	v_lshl_add_u32 v28, v28, 8, v196
	v_lshl_add_u32 v29, v29, 8, v193
	v_lshl_add_u32 v30, v30, 8, v194
	v_lshl_add_u32 v31, v31, 8, v195
	v_lshl_add_u32 v219, v219, 8, v196
	s_mov_b32 m0, s46
	s_nop 0
	global_load_lds_dwordx4 v0, s[28:29]
	global_load_lds_dwordx4 v1, s[28:29] offset:1024
	global_load_lds_dwordx4 v2, s[28:29] offset:2048
	global_load_lds_dwordx4 v3, s[28:29] offset:3072
	s_mov_b32 m0, s47
	s_nop 0
	global_load_lds_dwordx4 v4, s[28:29]
	global_load_lds_dwordx4 v5, s[28:29] offset:1024
	global_load_lds_dwordx4 v6, s[28:29] offset:2048
	global_load_lds_dwordx4 v7, s[28:29] offset:3072
	s_mov_b32 m0, s48
	s_nop 0
	global_load_lds_dwordx4 v8, s[28:29]
	global_load_lds_dwordx4 v9, s[28:29] offset:1024
	global_load_lds_dwordx4 v10, s[28:29] offset:2048
	global_load_lds_dwordx4 v11, s[28:29] offset:3072
	s_mov_b32 m0, s49
	s_nop 0
	global_load_lds_dwordx4 v12, s[28:29]
	global_load_lds_dwordx4 v13, s[28:29] offset:1024
	global_load_lds_dwordx4 v14, s[28:29] offset:2048
	global_load_lds_dwordx4 v15, s[28:29] offset:3072
	global_load_dword v209, v17, s[0:1]
	global_load_dword v209, v17, s[0:1]
	global_load_dword v209, v17, s[0:1]
	global_load_dword v209, v17, s[0:1]
	s_mov_b64 s[20:21], s[28:29]
	s_mov_b64 s[22:23], s[30:31]
	s_add_u32 s24, s28, 0x80
	s_addc_u32 s25, s29, 0
	s_add_u32 s26, s30, 0x80
	s_addc_u32 s27, s31, 0
	s_mov_b64 s[34:35], s[36:37]
	s_mov_b32 s44, s45
.Lattn_loop:
	s_waitcnt vmcnt(16)
	ds_read_b128 v[160:163], v180 offset:0
	ds_read_b128 v[164:167], v181 offset:0
	ds_read_b128 v[168:171], v180 offset:2048
	ds_read_b128 v[172:175], v181 offset:2048
	s_waitcnt lgkmcnt(0)
	s_mov_b32 m0, s46
	s_nop 0
	global_load_lds_dwordx4 v16, s[20:21]
	global_load_lds_dwordx4 v18, s[20:21] offset:1024
	global_load_lds_dwordx4 v19, s[20:21] offset:2048
	global_load_lds_dwordx4 v20, s[20:21] offset:3072
	v_mfma_f32_16x16x32_bf16 v[32:35], v[160:163], v[144:147], 0
	v_mfma_f32_16x16x32_bf16 v[36:39], v[168:171], v[144:147], 0
	v_mfma_f32_16x16x32_bf16 v[32:35], v[164:167], v[148:151], v[32:35]
	v_mfma_f32_16x16x32_bf16 v[36:39], v[172:175], v[148:151], v[36:39]
	s_waitcnt vmcnt(16)
	ds_read_b128 v[160:163], v180 offset:4096
	ds_read_b128 v[164:167], v181 offset:4096
	ds_read_b128 v[168:171], v180 offset:6144
	ds_read_b128 v[172:175], v181 offset:6144
	s_waitcnt lgkmcnt(0)
	s_mov_b32 m0, s47
	s_nop 0
	global_load_lds_dwordx4 v21, s[20:21]
	global_load_lds_dwordx4 v22, s[20:21] offset:1024
	global_load_lds_dwordx4 v23, s[20:21] offset:2048
	global_load_lds_dwordx4 v24, s[20:21] offset:3072
	v_mfma_f32_16x16x32_bf16 v[40:43], v[160:163], v[144:147], 0
	v_mfma_f32_16x16x32_bf16 v[44:47], v[168:171], v[144:147], 0
	v_mfma_f32_16x16x32_bf16 v[40:43], v[164:167], v[148:151], v[40:43]
	v_mfma_f32_16x16x32_bf16 v[44:47], v[172:175], v[148:151], v[44:47]
	s_waitcnt vmcnt(16)
	ds_read_b128 v[160:163], v180 offset:8192
	ds_read_b128 v[164:167], v181 offset:8192
	ds_read_b128 v[168:171], v180 offset:10240
	ds_read_b128 v[172:175], v181 offset:10240
	s_waitcnt lgkmcnt(0)
	s_mov_b32 m0, s48
	s_nop 0
	global_load_lds_dwordx4 v25, s[20:21]
	global_load_lds_dwordx4 v26, s[20:21] offset:1024
	global_load_lds_dwordx4 v27, s[20:21] offset:2048
	global_load_lds_dwordx4 v28, s[20:21] offset:3072
	v_mfma_f32_16x16x32_bf16 v[48:51], v[160:163], v[144:147], 0
	v_mfma_f32_16x16x32_bf16 v[52:55], v[168:171], v[144:147], 0
	v_mfma_f32_16x16x32_bf16 v[48:51], v[164:167], v[148:151], v[48:51]
	v_mfma_f32_16x16x32_bf16 v[52:55], v[172:175], v[148:151], v[52:55]
	s_waitcnt vmcnt(16)
	ds_read_b128 v[160:163], v180 offset:12288
	ds_read_b128 v[164:167], v181 offset:12288
	ds_read_b128 v[168:171], v180 offset:14336
	ds_read_b128 v[172:175], v181 offset:14336
	s_waitcnt lgkmcnt(0)
	s_mov_b32 m0, s49
	s_nop 0
	global_load_lds_dwordx4 v29, s[20:21]
	global_load_lds_dwordx4 v30, s[20:21] offset:1024
	global_load_lds_dwordx4 v31, s[20:21] offset:2048
	global_load_lds_dwordx4 v219, s[20:21] offset:3072
	v_mfma_f32_16x16x32_bf16 v[56:59], v[160:163], v[144:147], 0
	v_mfma_f32_16x16x32_bf16 v[60:63], v[168:171], v[144:147], 0
	v_mfma_f32_16x16x32_bf16 v[56:59], v[164:167], v[148:151], v[56:59]
	v_mfma_f32_16x16x32_bf16 v[60:63], v[172:175], v[148:151], v[60:63]
	s_waitcnt vmcnt(12)
	ds_read_b128 v[160:163], v180 offset:0
	ds_read_b128 v[164:167], v181 offset:0
	ds_read_b128 v[168:171], v180 offset:2048
	ds_read_b128 v[172:175], v181 offset:2048
	s_waitcnt lgkmcnt(0)
	s_mov_b32 m0, s46
	s_nop 0
	global_load_lds_dwordx4 v0, s[22:23]
	global_load_lds_dwordx4 v1, s[22:23] offset:1024
	global_load_lds_dwordx4 v2, s[22:23] offset:2048
	global_load_lds_dwordx4 v3, s[22:23] offset:3072
	v_mfma_f32_16x16x32_bf16 v[64:67], v[160:163], v[144:147], 0
	v_mfma_f32_16x16x32_bf16 v[68:71], v[168:171], v[144:147], 0
	v_mfma_f32_16x16x32_bf16 v[64:67], v[164:167], v[148:151], v[64:67]
	v_mfma_f32_16x16x32_bf16 v[68:71], v[172:175], v[148:151], v[68:71]
	s_waitcnt vmcnt(12)
; __device__ __forceinline__ void phase_attn(KP kp, int l, unsigned char* shm) {
;     ...
; #pragma unroll
;           for (int k8 = 0; k8 < 8; ++k8) {
;             f32x4 a = (f32x4){0.f, 0.f, 0.f, 0.f};
;             a = __builtin_amdgcn_mfma_f32_16x16x32_bf16(ka[k8][0], bq0, a, 0, 0, 0);
;             a = __builtin_amdgcn_mfma_f32_16x16x32_bf16(ka[k8][1], bq1, a, 0, 0, 0);
;             lg[hb * 8 + k8] = a;
;           }
;           __builtin_amdgcn_sched_barrier(0);
;         }
;       }
;       u32x4 vr[32];
; #pragma unroll
;       for (int i = 0; i < 16; ++i) {
;         const int idx = selw[i * 8 + ks8];
;         vr[i] = *(const u32x4*)(vbase + (size_t)idx * 128 + kvh * 64 + dc * 8);
;       }
;       float mx = -1e30f;
; #pragma unroll
;       for (int kb = 0; kb < 16; ++kb)
; #pragma unroll
;         for (int j = 0; j < 4; ++j) {
;           const int key = kb * 16 + kg * 4 + j;
;           lg[kb][j] = key < cnt ? lg[kb][j] : -1e30f;
;           mx = fmaxf(mx, lg[kb][j]);
;         }
;       mx = fmaxf(mx, __shfl_xor(mx, 16));
;       mx = fmaxf(mx, __shfl_xor(mx, 32));
	ds_read_b128 v[160:163], v180 offset:4096
	ds_read_b128 v[164:167], v181 offset:4096
	ds_read_b128 v[168:171], v180 offset:6144
	ds_read_b128 v[172:175], v181 offset:6144
	s_waitcnt lgkmcnt(0)
	s_mov_b32 m0, s47
	s_nop 0
	global_load_lds_dwordx4 v4, s[22:23]
	global_load_lds_dwordx4 v5, s[22:23] offset:1024
	global_load_lds_dwordx4 v6, s[22:23] offset:2048
	global_load_lds_dwordx4 v7, s[22:23] offset:3072
	v_mfma_f32_16x16x32_bf16 v[72:75], v[160:163], v[144:147], 0
	v_mfma_f32_16x16x32_bf16 v[76:79], v[168:171], v[144:147], 0
	v_mfma_f32_16x16x32_bf16 v[72:75], v[164:167], v[148:151], v[72:75]
	v_mfma_f32_16x16x32_bf16 v[76:79], v[172:175], v[148:151], v[76:79]
	s_waitcnt vmcnt(12)
	ds_read_b128 v[160:163], v180 offset:8192
	ds_read_b128 v[164:167], v181 offset:8192
	ds_read_b128 v[168:171], v180 offset:10240
	ds_read_b128 v[172:175], v181 offset:10240
	s_waitcnt lgkmcnt(0)
	s_mov_b32 m0, s48
	s_nop 0
	global_load_lds_dwordx4 v8, s[22:23]
	global_load_lds_dwordx4 v9, s[22:23] offset:1024
	global_load_lds_dwordx4 v10, s[22:23] offset:2048
	global_load_lds_dwordx4 v11, s[22:23] offset:3072
	v_mfma_f32_16x16x32_bf16 v[80:83], v[160:163], v[144:147], 0
	v_mfma_f32_16x16x32_bf16 v[84:87], v[168:171], v[144:147], 0
	v_mfma_f32_16x16x32_bf16 v[80:83], v[164:167], v[148:151], v[80:83]
	v_mfma_f32_16x16x32_bf16 v[84:87], v[172:175], v[148:151], v[84:87]
	s_waitcnt vmcnt(12)
	ds_read_b128 v[160:163], v180 offset:12288
	ds_read_b128 v[164:167], v181 offset:12288
	ds_read_b128 v[168:171], v180 offset:14336
	ds_read_b128 v[172:175], v181 offset:14336
	s_waitcnt lgkmcnt(0)
	s_mov_b32 m0, s49
	s_nop 0
	global_load_lds_dwordx4 v12, s[22:23]
	global_load_lds_dwordx4 v13, s[22:23] offset:1024
	global_load_lds_dwordx4 v14, s[22:23] offset:2048
	global_load_lds_dwordx4 v15, s[22:23] offset:3072
	v_mfma_f32_16x16x32_bf16 v[88:91], v[160:163], v[144:147], 0
	v_mfma_f32_16x16x32_bf16 v[92:95], v[168:171], v[144:147], 0
	v_mfma_f32_16x16x32_bf16 v[88:91], v[164:167], v[148:151], v[88:91]
	v_mfma_f32_16x16x32_bf16 v[92:95], v[172:175], v[148:151], v[92:95]
	s_nop 7
	s_nop 3
	s_cmp_ge_u32 s44, 0x100
	s_cbranch_scc1 .Lattn_nomask_4
	s_cmp_ge_u32 s44, 0xc0
	s_cbranch_scc1 .Lattn_m192_5
	s_cmp_ge_u32 s44, 0x80
	s_cbranch_scc1 .Lattn_m128_6
	v_mov_b32_e32 v48, 0xf149f2ca
	v_mov_b32_e32 v49, 0xf149f2ca
	v_mov_b32_e32 v50, 0xf149f2ca
	v_mov_b32_e32 v51, 0xf149f2ca
	v_mov_b32_e32 v52, 0xf149f2ca
	v_mov_b32_e32 v53, 0xf149f2ca
	v_mov_b32_e32 v54, 0xf149f2ca
	v_mov_b32_e32 v55, 0xf149f2ca
	v_mov_b32_e32 v56, 0xf149f2ca
	v_mov_b32_e32 v57, 0xf149f2ca
	v_mov_b32_e32 v58, 0xf149f2ca
	v_mov_b32_e32 v59, 0xf149f2ca
	v_mov_b32_e32 v60, 0xf149f2ca
	v_mov_b32_e32 v61, 0xf149f2ca
	v_mov_b32_e32 v62, 0xf149f2ca
	v_mov_b32_e32 v63, 0xf149f2ca
.Lattn_m128_6:
	v_mov_b32_e32 v64, 0xf149f2ca
	v_mov_b32_e32 v65, 0xf149f2ca
	v_mov_b32_e32 v66, 0xf149f2ca
	v_mov_b32_e32 v67, 0xf149f2ca
	v_mov_b32_e32 v68, 0xf149f2ca
	v_mov_b32_e32 v69, 0xf149f2ca
	v_mov_b32_e32 v70, 0xf149f2ca
	v_mov_b32_e32 v71, 0xf149f2ca
	v_mov_b32_e32 v72, 0xf149f2ca
	v_mov_b32_e32 v73, 0xf149f2ca
	v_mov_b32_e32 v74, 0xf149f2ca
	v_mov_b32_e32 v75, 0xf149f2ca
	v_mov_b32_e32 v76, 0xf149f2ca
	v_mov_b32_e32 v77, 0xf149f2ca
	v_mov_b32_e32 v78, 0xf149f2ca
	v_mov_b32_e32 v79, 0xf149f2ca
.Lattn_m192_5:
	v_mov_b32_e32 v80, 0xf149f2ca
	v_mov_b32_e32 v81, 0xf149f2ca
	v_mov_b32_e32 v82, 0xf149f2ca
	v_mov_b32_e32 v83, 0xf149f2ca
	v_mov_b32_e32 v84, 0xf149f2ca
	v_mov_b32_e32 v85, 0xf149f2ca
	v_mov_b32_e32 v86, 0xf149f2ca
	v_mov_b32_e32 v87, 0xf149f2ca
	v_mov_b32_e32 v88, 0xf149f2ca
	v_mov_b32_e32 v89, 0xf149f2ca
	v_mov_b32_e32 v90, 0xf149f2ca
	v_mov_b32_e32 v91, 0xf149f2ca
	v_mov_b32_e32 v92, 0xf149f2ca
	v_mov_b32_e32 v93, 0xf149f2ca
	v_mov_b32_e32 v94, 0xf149f2ca
	v_mov_b32_e32 v95, 0xf149f2ca
.Lattn_nomask_4:
	v_max3_f32 v176, v32, v33, v34
	v_max3_f32 v176, v176, v35, v36
	v_max3_f32 v176, v176, v37, v38
	v_max3_f32 v176, v176, v39, v40
	v_max3_f32 v176, v176, v41, v42
	v_max3_f32 v176, v176, v43, v44
	v_max3_f32 v176, v176, v45, v46
	v_max3_f32 v176, v176, v47, v48
	v_max3_f32 v176, v176, v49, v50
	v_max3_f32 v176, v176, v51, v52
	v_max3_f32 v176, v176, v53, v54
	v_max3_f32 v176, v176, v55, v56
	v_max3_f32 v176, v176, v57, v58
	v_max3_f32 v176, v176, v59, v60
	v_max3_f32 v176, v176, v61, v62
	v_max3_f32 v176, v176, v63, v64
	v_max3_f32 v176, v176, v65, v66
	v_max3_f32 v176, v176, v67, v68
	v_max3_f32 v176, v176, v69, v70
	v_max3_f32 v176, v176, v71, v72
	v_max3_f32 v176, v176, v73, v74
	v_max3_f32 v176, v176, v75, v76
	v_max3_f32 v176, v176, v77, v78
	v_max3_f32 v176, v176, v79, v80
	v_max3_f32 v176, v176, v81, v82
	v_max3_f32 v176, v176, v83, v84
	v_max3_f32 v176, v176, v85, v86
	v_max3_f32 v176, v176, v87, v88
	v_max3_f32 v176, v176, v89, v90
	v_max3_f32 v176, v176, v91, v92
	v_max3_f32 v176, v176, v93, v94
	v_max_f32_e32 v176, v176, v95
	ds_bpermute_b32 v197, v191, v176
	s_waitcnt lgkmcnt(0)
	v_max_f32_e32 v176, v176, v197
	ds_bpermute_b32 v197, v192, v176
	s_waitcnt lgkmcnt(0)
; __device__ __forceinline__ void phase_attn(KP kp, int l, unsigned char* shm) {
;     ...
;       mx = fmaxf(mx, __shfl_xor(mx, 16));
;       mx = fmaxf(mx, __shfl_xor(mx, 32));
;       float sum = 0.f;
; #pragma unroll
;       for (int kb = 0; kb < 16; ++kb)
; #pragma unroll
;         for (int j = 0; j < 4; ++j) { lg[kb][j] = __builtin_amdgcn_exp2f(lg[kb][j] - mx); sum += lg[kb][j]; }
;       sum += __shfl_xor(sum, 16);
;       sum += __shfl_xor(sum, 32);
;       const float inv = 1.f / sum;
;       bf16x8 pf[8];
; #pragma unroll
;       for (int s8 = 0; s8 < 8; ++s8) {
;         u32x4 pk;
;         pk[0] = cvt_pk_bf16(lg[2 * s8][0], lg[2 * s8][1]);
;         pk[1] = cvt_pk_bf16(lg[2 * s8][2], lg[2 * s8][3]);
;         pk[2] = cvt_pk_bf16(lg[2 * s8 + 1][0], lg[2 * s8 + 1][1]);
;         pk[3] = cvt_pk_bf16(lg[2 * s8 + 1][2], lg[2 * s8 + 1][3]);
;         pf[s8] = __builtin_bit_cast(bf16x8, pk);
;       }
	v_max_f32_e32 v176, v176, v197
	v_mov_b32_e32 v177, v176
	v_pk_add_f32 v[32:33], v[32:33], v[176:177] neg_lo:[0,1] neg_hi:[0,1]
	v_pk_add_f32 v[34:35], v[34:35], v[176:177] neg_lo:[0,1] neg_hi:[0,1]
	v_pk_add_f32 v[36:37], v[36:37], v[176:177] neg_lo:[0,1] neg_hi:[0,1]
	v_pk_add_f32 v[38:39], v[38:39], v[176:177] neg_lo:[0,1] neg_hi:[0,1]
	v_pk_add_f32 v[40:41], v[40:41], v[176:177] neg_lo:[0,1] neg_hi:[0,1]
	v_pk_add_f32 v[42:43], v[42:43], v[176:177] neg_lo:[0,1] neg_hi:[0,1]
	v_pk_add_f32 v[44:45], v[44:45], v[176:177] neg_lo:[0,1] neg_hi:[0,1]
	v_pk_add_f32 v[46:47], v[46:47], v[176:177] neg_lo:[0,1] neg_hi:[0,1]
	v_pk_add_f32 v[48:49], v[48:49], v[176:177] neg_lo:[0,1] neg_hi:[0,1]
	v_pk_add_f32 v[50:51], v[50:51], v[176:177] neg_lo:[0,1] neg_hi:[0,1]
	v_pk_add_f32 v[52:53], v[52:53], v[176:177] neg_lo:[0,1] neg_hi:[0,1]
	v_pk_add_f32 v[54:55], v[54:55], v[176:177] neg_lo:[0,1] neg_hi:[0,1]
	v_pk_add_f32 v[56:57], v[56:57], v[176:177] neg_lo:[0,1] neg_hi:[0,1]
	v_pk_add_f32 v[58:59], v[58:59], v[176:177] neg_lo:[0,1] neg_hi:[0,1]
	v_pk_add_f32 v[60:61], v[60:61], v[176:177] neg_lo:[0,1] neg_hi:[0,1]
	v_pk_add_f32 v[62:63], v[62:63], v[176:177] neg_lo:[0,1] neg_hi:[0,1]
	v_pk_add_f32 v[64:65], v[64:65], v[176:177] neg_lo:[0,1] neg_hi:[0,1]
	v_pk_add_f32 v[66:67], v[66:67], v[176:177] neg_lo:[0,1] neg_hi:[0,1]
	v_pk_add_f32 v[68:69], v[68:69], v[176:177] neg_lo:[0,1] neg_hi:[0,1]
	v_pk_add_f32 v[70:71], v[70:71], v[176:177] neg_lo:[0,1] neg_hi:[0,1]
	v_pk_add_f32 v[72:73], v[72:73], v[176:177] neg_lo:[0,1] neg_hi:[0,1]
	v_pk_add_f32 v[74:75], v[74:75], v[176:177] neg_lo:[0,1] neg_hi:[0,1]
	v_pk_add_f32 v[76:77], v[76:77], v[176:177] neg_lo:[0,1] neg_hi:[0,1]
	v_pk_add_f32 v[78:79], v[78:79], v[176:177] neg_lo:[0,1] neg_hi:[0,1]
	v_pk_add_f32 v[80:81], v[80:81], v[176:177] neg_lo:[0,1] neg_hi:[0,1]
	v_pk_add_f32 v[82:83], v[82:83], v[176:177] neg_lo:[0,1] neg_hi:[0,1]
	v_pk_add_f32 v[84:85], v[84:85], v[176:177] neg_lo:[0,1] neg_hi:[0,1]
	v_pk_add_f32 v[86:87], v[86:87], v[176:177] neg_lo:[0,1] neg_hi:[0,1]
	v_pk_add_f32 v[88:89], v[88:89], v[176:177] neg_lo:[0,1] neg_hi:[0,1]
	v_pk_add_f32 v[90:91], v[90:91], v[176:177] neg_lo:[0,1] neg_hi:[0,1]
	v_pk_add_f32 v[92:93], v[92:93], v[176:177] neg_lo:[0,1] neg_hi:[0,1]
	v_pk_add_f32 v[94:95], v[94:95], v[176:177] neg_lo:[0,1] neg_hi:[0,1]
	v_exp_f32_e32 v32, v32
	v_exp_f32_e32 v33, v33
	v_exp_f32_e32 v34, v34
	v_exp_f32_e32 v35, v35
	v_exp_f32_e32 v36, v36
	v_exp_f32_e32 v37, v37
	v_pk_add_f32 v[178:179], v[32:33], v[34:35]
	v_exp_f32_e32 v38, v38
	v_exp_f32_e32 v39, v39
	v_pk_add_f32 v[178:179], v[178:179], v[36:37]
	v_exp_f32_e32 v40, v40
	v_exp_f32_e32 v41, v41
	v_pk_add_f32 v[178:179], v[178:179], v[38:39]
	v_exp_f32_e32 v42, v42
	v_exp_f32_e32 v43, v43
	v_pk_add_f32 v[178:179], v[178:179], v[40:41]
	v_exp_f32_e32 v44, v44
	v_exp_f32_e32 v45, v45
	v_pk_add_f32 v[178:179], v[178:179], v[42:43]
	v_exp_f32_e32 v46, v46
	v_exp_f32_e32 v47, v47
	v_pk_add_f32 v[178:179], v[178:179], v[44:45]
	v_exp_f32_e32 v48, v48
	v_exp_f32_e32 v49, v49
	v_pk_add_f32 v[178:179], v[178:179], v[46:47]
	v_exp_f32_e32 v50, v50
	v_exp_f32_e32 v51, v51
	v_pk_add_f32 v[178:179], v[178:179], v[48:49]
	v_exp_f32_e32 v52, v52
	v_exp_f32_e32 v53, v53
	v_pk_add_f32 v[178:179], v[178:179], v[50:51]
	v_exp_f32_e32 v54, v54
	v_exp_f32_e32 v55, v55
	v_pk_add_f32 v[178:179], v[178:179], v[52:53]
	v_exp_f32_e32 v56, v56
	v_exp_f32_e32 v57, v57
	v_pk_add_f32 v[178:179], v[178:179], v[54:55]
	v_exp_f32_e32 v58, v58
	v_exp_f32_e32 v59, v59
	v_pk_add_f32 v[178:179], v[178:179], v[56:57]
	v_exp_f32_e32 v60, v60
	v_exp_f32_e32 v61, v61
	v_pk_add_f32 v[178:179], v[178:179], v[58:59]
	v_exp_f32_e32 v62, v62
	v_exp_f32_e32 v63, v63
	v_pk_add_f32 v[178:179], v[178:179], v[60:61]
	v_exp_f32_e32 v64, v64
	v_exp_f32_e32 v65, v65
	v_pk_add_f32 v[178:179], v[178:179], v[62:63]
	v_exp_f32_e32 v66, v66
	v_exp_f32_e32 v67, v67
	v_pk_add_f32 v[178:179], v[178:179], v[64:65]
	v_exp_f32_e32 v68, v68
	v_exp_f32_e32 v69, v69
	v_pk_add_f32 v[178:179], v[178:179], v[66:67]
	v_exp_f32_e32 v70, v70
	v_exp_f32_e32 v71, v71
	v_pk_add_f32 v[178:179], v[178:179], v[68:69]
	v_exp_f32_e32 v72, v72
	v_exp_f32_e32 v73, v73
	v_pk_add_f32 v[178:179], v[178:179], v[70:71]
	v_exp_f32_e32 v74, v74
	v_exp_f32_e32 v75, v75
	v_pk_add_f32 v[178:179], v[178:179], v[72:73]
	v_exp_f32_e32 v76, v76
	v_exp_f32_e32 v77, v77
	v_pk_add_f32 v[178:179], v[178:179], v[74:75]
	v_exp_f32_e32 v78, v78
	v_exp_f32_e32 v79, v79
	v_pk_add_f32 v[178:179], v[178:179], v[76:77]
	v_exp_f32_e32 v80, v80
	v_exp_f32_e32 v81, v81
	v_pk_add_f32 v[178:179], v[178:179], v[78:79]
	v_exp_f32_e32 v82, v82
	v_exp_f32_e32 v83, v83
	v_pk_add_f32 v[178:179], v[178:179], v[80:81]
	v_exp_f32_e32 v84, v84
	v_exp_f32_e32 v85, v85
	v_pk_add_f32 v[178:179], v[178:179], v[82:83]
	v_exp_f32_e32 v86, v86
	v_exp_f32_e32 v87, v87
	v_pk_add_f32 v[178:179], v[178:179], v[84:85]
	v_exp_f32_e32 v88, v88
	v_exp_f32_e32 v89, v89
	v_pk_add_f32 v[178:179], v[178:179], v[86:87]
	v_exp_f32_e32 v90, v90
	v_exp_f32_e32 v91, v91
	v_pk_add_f32 v[178:179], v[178:179], v[88:89]
	v_exp_f32_e32 v92, v92
	v_exp_f32_e32 v93, v93
	v_pk_add_f32 v[178:179], v[178:179], v[90:91]
	v_exp_f32_e32 v94, v94
	v_exp_f32_e32 v95, v95
	v_pk_add_f32 v[178:179], v[178:179], v[92:93]
	s_nop 0
	v_pk_add_f32 v[178:179], v[178:179], v[94:95]
	v_add_f32_e32 v210, v178, v179
	ds_bpermute_b32 v197, v191, v210
	v_cvt_pk_bf16_f32 v96, v32, v33
	v_cvt_pk_bf16_f32 v97, v34, v35
	v_cvt_pk_bf16_f32 v98, v36, v37
	v_cvt_pk_bf16_f32 v99, v38, v39
	v_cvt_pk_bf16_f32 v100, v40, v41
	v_cvt_pk_bf16_f32 v101, v42, v43
	v_cvt_pk_bf16_f32 v102, v44, v45
	v_cvt_pk_bf16_f32 v103, v46, v47
	v_cvt_pk_bf16_f32 v104, v48, v49
	v_cvt_pk_bf16_f32 v105, v50, v51
	v_cvt_pk_bf16_f32 v106, v52, v53
	v_cvt_pk_bf16_f32 v107, v54, v55
	v_cvt_pk_bf16_f32 v108, v56, v57
	v_cvt_pk_bf16_f32 v109, v58, v59
	v_cvt_pk_bf16_f32 v110, v60, v61
	v_cvt_pk_bf16_f32 v111, v62, v63
	s_waitcnt lgkmcnt(0)
; __device__ __forceinline__ void phase_attn(KP kp, int l, unsigned char* shm) {
;     ...
;       sum += __shfl_xor(sum, 16);
;       sum += __shfl_xor(sum, 32);
;       const float inv = 1.f / sum;
;       bf16x8 pf[8];
; #pragma unroll
;       for (int s8 = 0; s8 < 8; ++s8) {
;         u32x4 pk;
;         pk[0] = cvt_pk_bf16(lg[2 * s8][0], lg[2 * s8][1]);
;         pk[1] = cvt_pk_bf16(lg[2 * s8][2], lg[2 * s8][3]);
;         pk[2] = cvt_pk_bf16(lg[2 * s8 + 1][0], lg[2 * s8 + 1][1]);
;         pk[3] = cvt_pk_bf16(lg[2 * s8 + 1][2], lg[2 * s8 + 1][3]);
;         pf[s8] = __builtin_bit_cast(bf16x8, pk);
;       }
;       f32x4 oacc[4];
; #pragma unroll
;       for (int c = 0; c < 4; ++c) oacc[c] = (f32x4){0.f, 0.f, 0.f, 0.f};
;       for (int repV = 0; repV < ((PROBE & 256) ? 2 : 1); ++repV)
;       {
;         if (repV) {
; #pragma unroll
;           for (int c = 0; c < 4; ++c) oacc[c] = (f32x4){0.f, 0.f, 0.f, 0.f};
;         }
; #pragma unroll
;         for (int i = 16; i < 32; ++i) {
;           const int idx = selw[i * 8 + ks8];
;           vr[i] = *(const u32x4*)(vbase + (size_t)idx * 128 + kvh * 64 + dc * 8);
;         }
; #pragma unroll
;         for (int s8 = 0; s8 < 8; ++s8) {
; #pragma unroll
;           for (int it = 0; it < 4; ++it) *(u32x4*)(tileb + (it * 8 + ks8) * 144 + dc * 16) = vr[s8 * 4 + it];
;           u32x2 t0, t1, t2, t3, t4, t5, t6, t7;
;           asm volatile(
;               "ds_read_b64_tr_b16 %0, %8\n\tds_read_b64_tr_b16 %1, %8 offset:2304\n\t"
;               "ds_read_b64_tr_b16 %2, %8 offset:32\n\tds_read_b64_tr_b16 %3, %8 offset:2336\n\t"
;               "ds_read_b64_tr_b16 %4, %8 offset:64\n\tds_read_b64_tr_b16 %5, %8 offset:2368\n\t"
;               "ds_read_b64_tr_b16 %6, %8 offset:96\n\tds_read_b64_tr_b16 %7, %8 offset:2400\n\t"
;               "s_waitcnt lgkmcnt(0)"
;               : "=&v"(t0), "=&v"(t1), "=&v"(t2), "=&v"(t3), "=&v"(t4), "=&v"(t5), "=&v"(t6), "=&v"(t7)
;               : "v"(tr_addr)
;               : "memory");
;           const bf16x8 a0 = __builtin_bit_cast(bf16x8, (u32x4){t0[0], t0[1], t1[0], t1[1]});
;           const bf16x8 a1 = __builtin_bit_cast(bf16x8, (u32x4){t2[0], t2[1], t3[0], t3[1]});
;           const bf16x8 a2 = __builtin_bit_cast(bf16x8, (u32x4){t4[0], t4[1], t5[0], t5[1]});
;           const bf16x8 a3 = __builtin_bit_cast(bf16x8, (u32x4){t6[0], t6[1], t7[0], t7[1]});
	v_add_f32_e32 v210, v210, v197
	ds_bpermute_b32 v197, v192, v210
	v_cvt_pk_bf16_f32 v112, v64, v65
	v_cvt_pk_bf16_f32 v113, v66, v67
	v_cvt_pk_bf16_f32 v114, v68, v69
	v_cvt_pk_bf16_f32 v115, v70, v71
	v_cvt_pk_bf16_f32 v116, v72, v73
	v_cvt_pk_bf16_f32 v117, v74, v75
	v_cvt_pk_bf16_f32 v118, v76, v77
	v_cvt_pk_bf16_f32 v119, v78, v79
	v_cvt_pk_bf16_f32 v120, v80, v81
	v_cvt_pk_bf16_f32 v121, v82, v83
	v_cvt_pk_bf16_f32 v122, v84, v85
	v_cvt_pk_bf16_f32 v123, v86, v87
	v_cvt_pk_bf16_f32 v124, v88, v89
	v_cvt_pk_bf16_f32 v125, v90, v91
	v_cvt_pk_bf16_f32 v126, v92, v93
	v_cvt_pk_bf16_f32 v127, v94, v95
	s_waitcnt lgkmcnt(0)
	v_add_f32_e32 v210, v210, v197
	v_rcp_f32_e32 v208, v210
	s_waitcnt vmcnt(12)
	ds_read_b64_tr_b16 v[160:161], v182 offset:0
	ds_read_b64_tr_b16 v[162:163], v182 offset:2048
	ds_read_b64_tr_b16 v[164:165], v183 offset:0
	ds_read_b64_tr_b16 v[166:167], v183 offset:2048
	ds_read_b64_tr_b16 v[168:169], v184 offset:0
	ds_read_b64_tr_b16 v[170:171], v184 offset:2048
	ds_read_b64_tr_b16 v[172:173], v185 offset:0
	ds_read_b64_tr_b16 v[174:175], v185 offset:2048
	s_waitcnt lgkmcnt(0)
	s_mov_b32 m0, s46
	s_nop 0
	global_load_lds_dwordx4 v16, s[22:23]
	global_load_lds_dwordx4 v18, s[22:23] offset:1024
	global_load_lds_dwordx4 v19, s[22:23] offset:2048
	global_load_lds_dwordx4 v20, s[22:23] offset:3072
	v_mfma_f32_16x16x32_bf16 v[128:131], v[160:163], v[96:99], 0
	v_mfma_f32_16x16x32_bf16 v[132:135], v[164:167], v[96:99], 0
	v_mfma_f32_16x16x32_bf16 v[136:139], v[168:171], v[96:99], 0
	v_mfma_f32_16x16x32_bf16 v[140:143], v[172:175], v[96:99], 0
	s_waitcnt vmcnt(12)
	ds_read_b64_tr_b16 v[160:161], v182 offset:4096
	ds_read_b64_tr_b16 v[162:163], v182 offset:6144
	ds_read_b64_tr_b16 v[164:165], v183 offset:4096
	ds_read_b64_tr_b16 v[166:167], v183 offset:6144
	ds_read_b64_tr_b16 v[168:169], v184 offset:4096
	ds_read_b64_tr_b16 v[170:171], v184 offset:6144
	ds_read_b64_tr_b16 v[172:173], v185 offset:4096
	ds_read_b64_tr_b16 v[174:175], v185 offset:6144
	s_waitcnt lgkmcnt(0)
	s_mov_b32 m0, s47
	s_nop 0
	global_load_lds_dwordx4 v21, s[22:23]
	global_load_lds_dwordx4 v22, s[22:23] offset:1024
	global_load_lds_dwordx4 v23, s[22:23] offset:2048
	global_load_lds_dwordx4 v24, s[22:23] offset:3072
	v_mfma_f32_16x16x32_bf16 v[128:131], v[160:163], v[100:103], v[128:131]
	v_mfma_f32_16x16x32_bf16 v[132:135], v[164:167], v[100:103], v[132:135]
	v_mfma_f32_16x16x32_bf16 v[136:139], v[168:171], v[100:103], v[136:139]
	v_mfma_f32_16x16x32_bf16 v[140:143], v[172:175], v[100:103], v[140:143]
	s_waitcnt vmcnt(12)
	ds_read_b64_tr_b16 v[160:161], v182 offset:8192
	ds_read_b64_tr_b16 v[162:163], v182 offset:10240
	ds_read_b64_tr_b16 v[164:165], v183 offset:8192
	ds_read_b64_tr_b16 v[166:167], v183 offset:10240
	ds_read_b64_tr_b16 v[168:169], v184 offset:8192
	ds_read_b64_tr_b16 v[170:171], v184 offset:10240
	ds_read_b64_tr_b16 v[172:173], v185 offset:8192
	ds_read_b64_tr_b16 v[174:175], v185 offset:10240
	s_waitcnt lgkmcnt(0)
	s_mov_b32 m0, s48
	s_nop 0
	global_load_lds_dwordx4 v25, s[22:23]
	global_load_lds_dwordx4 v26, s[22:23] offset:1024
	global_load_lds_dwordx4 v27, s[22:23] offset:2048
	global_load_lds_dwordx4 v28, s[22:23] offset:3072
	v_mfma_f32_16x16x32_bf16 v[128:131], v[160:163], v[104:107], v[128:131]
	v_mfma_f32_16x16x32_bf16 v[132:135], v[164:167], v[104:107], v[132:135]
	v_mfma_f32_16x16x32_bf16 v[136:139], v[168:171], v[104:107], v[136:139]
	v_mfma_f32_16x16x32_bf16 v[140:143], v[172:175], v[104:107], v[140:143]
	s_waitcnt vmcnt(12)
	ds_read_b64_tr_b16 v[160:161], v182 offset:12288
	ds_read_b64_tr_b16 v[162:163], v182 offset:14336
	ds_read_b64_tr_b16 v[164:165], v183 offset:12288
	ds_read_b64_tr_b16 v[166:167], v183 offset:14336
	ds_read_b64_tr_b16 v[168:169], v184 offset:12288
	ds_read_b64_tr_b16 v[170:171], v184 offset:14336
	ds_read_b64_tr_b16 v[172:173], v185 offset:12288
	ds_read_b64_tr_b16 v[174:175], v185 offset:14336
	s_waitcnt lgkmcnt(0)
	s_mov_b32 m0, s49
	s_nop 0
	global_load_lds_dwordx4 v29, s[22:23]
	global_load_lds_dwordx4 v30, s[22:23] offset:1024
	global_load_lds_dwordx4 v31, s[22:23] offset:2048
	global_load_lds_dwordx4 v219, s[22:23] offset:3072
	v_mfma_f32_16x16x32_bf16 v[128:131], v[160:163], v[108:111], v[128:131]
	v_mfma_f32_16x16x32_bf16 v[132:135], v[164:167], v[108:111], v[132:135]
	v_mfma_f32_16x16x32_bf16 v[136:139], v[168:171], v[108:111], v[136:139]
	v_mfma_f32_16x16x32_bf16 v[140:143], v[172:175], v[108:111], v[140:143]
	s_waitcnt vmcnt(12)
	ds_read_b64_tr_b16 v[160:161], v182 offset:0
	ds_read_b64_tr_b16 v[162:163], v182 offset:2048
	ds_read_b64_tr_b16 v[164:165], v183 offset:0
	ds_read_b64_tr_b16 v[166:167], v183 offset:2048
	ds_read_b64_tr_b16 v[168:169], v184 offset:0
	ds_read_b64_tr_b16 v[170:171], v184 offset:2048
	ds_read_b64_tr_b16 v[172:173], v185 offset:0
	ds_read_b64_tr_b16 v[174:175], v185 offset:2048
	s_waitcnt lgkmcnt(0)
; __device__ __forceinline__ void phase_attn(KP kp, int l, unsigned char* shm) {
;     ...
;         for (int i = 16; i < 32; ++i) {
;           const int idx = selw[i * 8 + ks8];
;           vr[i] = *(const u32x4*)(vbase + (size_t)idx * 128 + kvh * 64 + dc * 8);
;         }
; #pragma unroll
;         for (int s8 = 0; s8 < 8; ++s8) {
; #pragma unroll
;           for (int it = 0; it < 4; ++it) *(u32x4*)(tileb + (it * 8 + ks8) * 144 + dc * 16) = vr[s8 * 4 + it];
;           u32x2 t0, t1, t2, t3, t4, t5, t6, t7;
;           asm volatile(
;               "ds_read_b64_tr_b16 %0, %8\n\tds_read_b64_tr_b16 %1, %8 offset:2304\n\t"
;               "ds_read_b64_tr_b16 %2, %8 offset:32\n\tds_read_b64_tr_b16 %3, %8 offset:2336\n\t"
;               "ds_read_b64_tr_b16 %4, %8 offset:64\n\tds_read_b64_tr_b16 %5, %8 offset:2368\n\t"
;               "ds_read_b64_tr_b16 %6, %8 offset:96\n\tds_read_b64_tr_b16 %7, %8 offset:2400\n\t"
;               "s_waitcnt lgkmcnt(0)"
;               : "=&v"(t0), "=&v"(t1), "=&v"(t2), "=&v"(t3), "=&v"(t4), "=&v"(t5), "=&v"(t6), "=&v"(t7)
;               : "v"(tr_addr)
;               : "memory");
;           const bf16x8 a0 = __builtin_bit_cast(bf16x8, (u32x4){t0[0], t0[1], t1[0], t1[1]});
;           const bf16x8 a1 = __builtin_bit_cast(bf16x8, (u32x4){t2[0], t2[1], t3[0], t3[1]});
;           const bf16x8 a2 = __builtin_bit_cast(bf16x8, (u32x4){t4[0], t4[1], t5[0], t5[1]});
;           const bf16x8 a3 = __builtin_bit_cast(bf16x8, (u32x4){t6[0], t6[1], t7[0], t7[1]});
;           oacc[0] = __builtin_amdgcn_mfma_f32_16x16x32_bf16(a0, pf[s8], oacc[0], 0, 0, 0);
;           oacc[1] = __builtin_amdgcn_mfma_f32_16x16x32_bf16(a1, pf[s8], oacc[1], 0, 0, 0);
;           oacc[2] = __builtin_amdgcn_mfma_f32_16x16x32_bf16(a2, pf[s8], oacc[2], 0, 0, 0);
;           oacc[3] = __builtin_amdgcn_mfma_f32_16x16x32_bf16(a3, pf[s8], oacc[3], 0, 0, 0);
;           if (kvh == 0 && s8 == 3) {
; #pragma unroll
;             for (int k8 = 0; k8 < 8; ++k8) {
;               const int idx = selw[k8 * 16 + nn];
;               const bf16_t* kp = kbase + (size_t)idx * 128 + 64 + kg * 8;
;               kpre[k8][0] = *(const bf16x8*)kp;
;               kpre[k8][1] = *(const bf16x8*)(kp + 32);
;             }
;           }
;         }
;         __builtin_amdgcn_sched_barrier(0);
;       }
;       if (nn < 4) {
; #pragma unroll
;         for (int c = 0; c < 4; ++c) {
	s_mov_b32 m0, s46
	s_nop 0
	global_load_lds_dwordx4 v0, s[24:25]
	global_load_lds_dwordx4 v1, s[24:25] offset:1024
	global_load_lds_dwordx4 v2, s[24:25] offset:2048
	global_load_lds_dwordx4 v3, s[24:25] offset:3072
	v_mfma_f32_16x16x32_bf16 v[128:131], v[160:163], v[112:115], v[128:131]
	v_mfma_f32_16x16x32_bf16 v[132:135], v[164:167], v[112:115], v[132:135]
	v_mfma_f32_16x16x32_bf16 v[136:139], v[168:171], v[112:115], v[136:139]
	v_mfma_f32_16x16x32_bf16 v[140:143], v[172:175], v[112:115], v[140:143]
	s_waitcnt vmcnt(12)
	ds_read_b64_tr_b16 v[160:161], v182 offset:4096
	ds_read_b64_tr_b16 v[162:163], v182 offset:6144
	ds_read_b64_tr_b16 v[164:165], v183 offset:4096
	ds_read_b64_tr_b16 v[166:167], v183 offset:6144
	ds_read_b64_tr_b16 v[168:169], v184 offset:4096
	ds_read_b64_tr_b16 v[170:171], v184 offset:6144
	ds_read_b64_tr_b16 v[172:173], v185 offset:4096
	ds_read_b64_tr_b16 v[174:175], v185 offset:6144
	s_waitcnt lgkmcnt(0)
	s_mov_b32 m0, s47
	s_nop 0
	global_load_lds_dwordx4 v4, s[24:25]
	global_load_lds_dwordx4 v5, s[24:25] offset:1024
	global_load_lds_dwordx4 v6, s[24:25] offset:2048
	global_load_lds_dwordx4 v7, s[24:25] offset:3072
	v_mfma_f32_16x16x32_bf16 v[128:131], v[160:163], v[116:119], v[128:131]
	v_mfma_f32_16x16x32_bf16 v[132:135], v[164:167], v[116:119], v[132:135]
	v_mfma_f32_16x16x32_bf16 v[136:139], v[168:171], v[116:119], v[136:139]
	v_mfma_f32_16x16x32_bf16 v[140:143], v[172:175], v[116:119], v[140:143]
	s_waitcnt vmcnt(12)
	ds_read_b64_tr_b16 v[160:161], v182 offset:8192
	ds_read_b64_tr_b16 v[162:163], v182 offset:10240
	ds_read_b64_tr_b16 v[164:165], v183 offset:8192
	ds_read_b64_tr_b16 v[166:167], v183 offset:10240
	ds_read_b64_tr_b16 v[168:169], v184 offset:8192
	ds_read_b64_tr_b16 v[170:171], v184 offset:10240
	ds_read_b64_tr_b16 v[172:173], v185 offset:8192
	ds_read_b64_tr_b16 v[174:175], v185 offset:10240
	s_waitcnt lgkmcnt(0)
	s_mov_b32 m0, s48
	s_nop 0
	global_load_lds_dwordx4 v8, s[24:25]
	global_load_lds_dwordx4 v9, s[24:25] offset:1024
	global_load_lds_dwordx4 v10, s[24:25] offset:2048
	global_load_lds_dwordx4 v11, s[24:25] offset:3072
	v_mfma_f32_16x16x32_bf16 v[128:131], v[160:163], v[120:123], v[128:131]
	v_mfma_f32_16x16x32_bf16 v[132:135], v[164:167], v[120:123], v[132:135]
	v_mfma_f32_16x16x32_bf16 v[136:139], v[168:171], v[120:123], v[136:139]
	v_mfma_f32_16x16x32_bf16 v[140:143], v[172:175], v[120:123], v[140:143]
	s_waitcnt vmcnt(12)
	ds_read_b64_tr_b16 v[160:161], v182 offset:12288
	ds_read_b64_tr_b16 v[162:163], v182 offset:14336
	ds_read_b64_tr_b16 v[164:165], v183 offset:12288
	ds_read_b64_tr_b16 v[166:167], v183 offset:14336
	ds_read_b64_tr_b16 v[168:169], v184 offset:12288
	ds_read_b64_tr_b16 v[170:171], v184 offset:14336
	ds_read_b64_tr_b16 v[172:173], v185 offset:12288
	ds_read_b64_tr_b16 v[174:175], v185 offset:14336
	s_waitcnt lgkmcnt(0)
	s_mov_b32 m0, s49
	s_nop 0
	global_load_lds_dwordx4 v12, s[24:25]
	global_load_lds_dwordx4 v13, s[24:25] offset:1024
	global_load_lds_dwordx4 v14, s[24:25] offset:2048
	global_load_lds_dwordx4 v15, s[24:25] offset:3072
	v_mfma_f32_16x16x32_bf16 v[128:131], v[160:163], v[124:127], v[128:131]
	v_mfma_f32_16x16x32_bf16 v[132:135], v[164:167], v[124:127], v[132:135]
	v_mfma_f32_16x16x32_bf16 v[136:139], v[168:171], v[124:127], v[136:139]
	v_mfma_f32_16x16x32_bf16 v[140:143], v[172:175], v[124:127], v[140:143]
	s_nop 7
	s_nop 3
	v_mul_f32_e32 v128, v208, v128
	v_mul_f32_e32 v129, v208, v129
	v_mul_f32_e32 v130, v208, v130
	v_mul_f32_e32 v131, v208, v131
	v_cvt_pk_bf16_f32 v200, v128, v129
	v_cvt_pk_bf16_f32 v201, v130, v131
	v_mul_f32_e32 v132, v208, v132
	v_mul_f32_e32 v133, v208, v133
	v_mul_f32_e32 v134, v208, v134
	v_mul_f32_e32 v135, v208, v135
	v_cvt_pk_bf16_f32 v202, v132, v133
	v_cvt_pk_bf16_f32 v203, v134, v135
	v_mul_f32_e32 v136, v208, v136
	v_mul_f32_e32 v137, v208, v137
	v_mul_f32_e32 v138, v208, v138
	v_mul_f32_e32 v139, v208, v139
	v_cvt_pk_bf16_f32 v204, v136, v137
	v_cvt_pk_bf16_f32 v205, v138, v139
	v_mul_f32_e32 v140, v208, v140
	v_mul_f32_e32 v141, v208, v141
	v_mul_f32_e32 v142, v208, v142
	v_mul_f32_e32 v143, v208, v143
	v_cvt_pk_bf16_f32 v206, v140, v141
	v_cvt_pk_bf16_f32 v207, v142, v143
	s_mov_b64 exec, s[42:43]
	global_store_dwordx2 v190, v[200:201], s[34:35] offset:0
	global_store_dwordx2 v190, v[202:203], s[34:35] offset:32
	global_store_dwordx2 v190, v[204:205], s[34:35] offset:64
	global_store_dwordx2 v190, v[206:207], s[34:35] offset:96
	s_mov_b64 exec, -1
	s_waitcnt vmcnt(16)
	ds_read_b128 v[160:163], v180 offset:0
	ds_read_b128 v[164:167], v181 offset:0
	ds_read_b128 v[168:171], v180 offset:2048
	ds_read_b128 v[172:175], v181 offset:2048
	s_add_i32 s50, s2, s4
	s_cmp_lt_i32 s50, 0x8200
	s_cselect_b32 s53, s50, s2
	s_mov_b32 s51, s53
	s_cmp_lg_u32 s5, 0
	s_cbranch_scc1 .Lattn_noswz_7
	s_cmp_ge_i32 s53, 0x8000
	s_cbranch_scc1 .Lattn_noswz_7
	s_lshl_b32 s6, s53, 9
	s_and_b32 s6, s6, 0x7000
	s_lshr_b32 s7, s53, 3
	s_and_b32 s8, s7, 0xffffff00
	s_and_b32 s7, s7, 0xf8
	s_or_b32 s6, s6, s8
	s_or_b32 s6, s6, s7
	s_and_b32 s7, s53, 7
	s_or_b32 s51, s6, s7

; __device__ __forceinline__ void phase_attn(KP kp, int l, unsigned char* shm) {
;     ...
;     const bf16_t *kbase, *vbase;
;     int n;
;     if (r < MP) {
;       const int b = r >> 12, t = r & 4095;
;       kbase = (const bf16_t*)(ws + W_KP) + (size_t)b * 4096 * 128;
;       vbase = (const bf16_t*)(ws + W_VP) + (size_t)b * 4096 * 128;
;       n = ((t >> 6) + 1) * 64;
;     } else {
;       const int sb = (r - MP) >> 5;
;       kbase = (const bf16_t*)(ws + W_KS) + (size_t)(l * 16 + sb) * 2080 * 128;
;       vbase = (const bf16_t*)(ws + W_VS) + (size_t)(l * 16 + sb) * 2080 * 128;
;       n = 2080;
;     }
;     const int cnt = n < 256 ? n : 256;
;     {
;       u32x2 sv = *(const u32x2*)(SEL + (size_t)r * 256 + lane * 4);
;     ...
;         for (int hb = 0; hb < 2; ++hb) {
;           bf16x8 ka[8][2];
;           if (kvh == 1 && hb == 0) {
; #pragma unroll
;             for (int k8 = 0; k8 < 8; ++k8) { ka[k8][0] = kpre[k8][0]; ka[k8][1] = kpre[k8][1]; }
;           } else {
; #pragma unroll
;             for (int k8 = 0; k8 < 8; ++k8) {
;               const int idx = selw[(hb * 8 + k8) * 16 + nn];
;               const bf16_t* kp = kbase + (size_t)idx * 128 + kvh * 64 + kg * 8;
;               ka[k8][0] = *(const bf16x8*)kp;
;               ka[k8][1] = *(const bf16x8*)(kp + 32);
;             }
;           }
;           __builtin_amdgcn_sched_barrier(0);
; #pragma unroll
;           for (int k8 = 0; k8 < 8; ++k8) {
;             f32x4 a = (f32x4){0.f, 0.f, 0.f, 0.f};
;             a = __builtin_amdgcn_mfma_f32_16x16x32_bf16(ka[k8][0], bq0, a, 0, 0, 0);
;             a = __builtin_amdgcn_mfma_f32_16x16x32_bf16(ka[k8][1], bq1, a, 0, 0, 0);
;             lg[hb * 8 + k8] = a;
;           }
;           __builtin_amdgcn_sched_barrier(0);
;         }
;       }
;       u32x4 vr[32];
; #pragma unroll
;       for (int i = 0; i < 16; ++i) {
;         const int idx = selw[i * 8 + ks8];
;         vr[i] = *(const u32x4*)(vbase + (size_t)idx * 128 + kvh * 64 + dc * 8);
;       }
;       float mx = -1e30f;
; #pragma unroll
;       for (int kb = 0; kb < 16; ++kb)
; #pragma unroll
;         for (int j = 0; j < 4; ++j) {
;           const int key = kb * 16 + kg * 4 + j;
;           lg[kb][j] = key < cnt ? lg[kb][j] : -1e30f;
;           mx = fmaxf(mx, lg[kb][j]);
;         }
.Lattn_join_9:
	s_add_u32 s28, s0, s7
	s_addc_u32 s29, s1, 0
	s_add_u32 s30, s0, s8
	s_addc_u32 s31, s1, 0
	s_lshl_b32 s6, s51, 9
	s_add_u32 s6, s6, 0x1b3c2000
	s_add_u32 s38, s0, s6
	s_addc_u32 s39, s1, 0
	s_lshl_b32 s6, s51, 10
	s_add_u32 s7, s6, 0x7ac0000
	s_add_u32 s40, s0, s7
	s_addc_u32 s41, s1, 0
	s_add_u32 s7, s6, 0x1c402000
	s_add_u32 s36, s0, s7
	s_addc_u32 s37, s1, 0
	global_load_dwordx2 v[198:199], v188, s[38:39]
	s_waitcnt lgkmcnt(0)
	s_mov_b32 m0, s46
	s_nop 0
	global_load_lds_dwordx4 v16, s[24:25]
	global_load_lds_dwordx4 v18, s[24:25] offset:1024
	global_load_lds_dwordx4 v19, s[24:25] offset:2048
	global_load_lds_dwordx4 v20, s[24:25] offset:3072
	v_mfma_f32_16x16x32_bf16 v[32:35], v[160:163], v[152:155], 0
	v_mfma_f32_16x16x32_bf16 v[36:39], v[168:171], v[152:155], 0
	v_mfma_f32_16x16x32_bf16 v[32:35], v[164:167], v[156:159], v[32:35]
	v_mfma_f32_16x16x32_bf16 v[36:39], v[172:175], v[156:159], v[36:39]
	s_waitcnt vmcnt(17)
	ds_read_b128 v[160:163], v180 offset:4096
	ds_read_b128 v[164:167], v181 offset:4096
	ds_read_b128 v[168:171], v180 offset:6144
	ds_read_b128 v[172:175], v181 offset:6144
	s_waitcnt lgkmcnt(0)
	s_mov_b32 m0, s47
	s_nop 0
	global_load_lds_dwordx4 v21, s[24:25]
	global_load_lds_dwordx4 v22, s[24:25] offset:1024
	global_load_lds_dwordx4 v23, s[24:25] offset:2048
	global_load_lds_dwordx4 v24, s[24:25] offset:3072
	v_mfma_f32_16x16x32_bf16 v[40:43], v[160:163], v[152:155], 0
	v_mfma_f32_16x16x32_bf16 v[44:47], v[168:171], v[152:155], 0
	v_mfma_f32_16x16x32_bf16 v[40:43], v[164:167], v[156:159], v[40:43]
	v_mfma_f32_16x16x32_bf16 v[44:47], v[172:175], v[156:159], v[44:47]
	s_waitcnt vmcnt(17)
	ds_read_b128 v[160:163], v180 offset:8192
	ds_read_b128 v[164:167], v181 offset:8192
	ds_read_b128 v[168:171], v180 offset:10240
	ds_read_b128 v[172:175], v181 offset:10240
	s_waitcnt lgkmcnt(0)
	s_mov_b32 m0, s48
	s_nop 0
	global_load_lds_dwordx4 v25, s[24:25]
	global_load_lds_dwordx4 v26, s[24:25] offset:1024
	global_load_lds_dwordx4 v27, s[24:25] offset:2048
	global_load_lds_dwordx4 v28, s[24:25] offset:3072
	v_mfma_f32_16x16x32_bf16 v[48:51], v[160:163], v[152:155], 0
	v_mfma_f32_16x16x32_bf16 v[52:55], v[168:171], v[152:155], 0
	v_mfma_f32_16x16x32_bf16 v[48:51], v[164:167], v[156:159], v[48:51]
	v_mfma_f32_16x16x32_bf16 v[52:55], v[172:175], v[156:159], v[52:55]
	s_waitcnt vmcnt(17)
	ds_read_b128 v[160:163], v180 offset:12288
	ds_read_b128 v[164:167], v181 offset:12288
	ds_read_b128 v[168:171], v180 offset:14336
	ds_read_b128 v[172:175], v181 offset:14336
	s_waitcnt lgkmcnt(0)
	s_mov_b32 m0, s49
	s_nop 0
	global_load_lds_dwordx4 v29, s[24:25]
	global_load_lds_dwordx4 v30, s[24:25] offset:1024
	global_load_lds_dwordx4 v31, s[24:25] offset:2048
	global_load_lds_dwordx4 v219, s[24:25] offset:3072
	v_mfma_f32_16x16x32_bf16 v[56:59], v[160:163], v[152:155], 0
	v_mfma_f32_16x16x32_bf16 v[60:63], v[168:171], v[152:155], 0
	v_mfma_f32_16x16x32_bf16 v[56:59], v[164:167], v[156:159], v[56:59]
	v_mfma_f32_16x16x32_bf16 v[60:63], v[172:175], v[156:159], v[60:63]
	s_waitcnt vmcnt(12)
	ds_read_b128 v[160:163], v180 offset:0
	ds_read_b128 v[164:167], v181 offset:0
	ds_read_b128 v[168:171], v180 offset:2048
	ds_read_b128 v[172:175], v181 offset:2048
	s_waitcnt lgkmcnt(0)
	s_mov_b32 m0, s46
	s_nop 0
	global_load_lds_dwordx4 v0, s[26:27]
	global_load_lds_dwordx4 v1, s[26:27] offset:1024
	global_load_lds_dwordx4 v2, s[26:27] offset:2048
	global_load_lds_dwordx4 v3, s[26:27] offset:3072
	v_mfma_f32_16x16x32_bf16 v[64:67], v[160:163], v[152:155], 0
	v_mfma_f32_16x16x32_bf16 v[68:71], v[168:171], v[152:155], 0
	v_mfma_f32_16x16x32_bf16 v[64:67], v[164:167], v[156:159], v[64:67]
	v_mfma_f32_16x16x32_bf16 v[68:71], v[172:175], v[156:159], v[68:71]
	s_waitcnt vmcnt(12)
	ds_read_b128 v[160:163], v180 offset:4096
	ds_read_b128 v[164:167], v181 offset:4096
	ds_read_b128 v[168:171], v180 offset:6144
	ds_read_b128 v[172:175], v181 offset:6144
	s_waitcnt lgkmcnt(0)
	s_mov_b32 m0, s47
	s_nop 0
	global_load_lds_dwordx4 v4, s[26:27]
	global_load_lds_dwordx4 v5, s[26:27] offset:1024
	global_load_lds_dwordx4 v6, s[26:27] offset:2048
	global_load_lds_dwordx4 v7, s[26:27] offset:3072
	v_mfma_f32_16x16x32_bf16 v[72:75], v[160:163], v[152:155], 0
	v_mfma_f32_16x16x32_bf16 v[76:79], v[168:171], v[152:155], 0
	v_mfma_f32_16x16x32_bf16 v[72:75], v[164:167], v[156:159], v[72:75]
	v_mfma_f32_16x16x32_bf16 v[76:79], v[172:175], v[156:159], v[76:79]
	s_waitcnt vmcnt(12)
	ds_read_b128 v[160:163], v180 offset:8192
	ds_read_b128 v[164:167], v181 offset:8192
	ds_read_b128 v[168:171], v180 offset:10240
	ds_read_b128 v[172:175], v181 offset:10240
	s_waitcnt lgkmcnt(0)
	s_mov_b32 m0, s48
	s_nop 0
	global_load_lds_dwordx4 v8, s[26:27]
	global_load_lds_dwordx4 v9, s[26:27] offset:1024
	global_load_lds_dwordx4 v10, s[26:27] offset:2048
	global_load_lds_dwordx4 v11, s[26:27] offset:3072
	v_mfma_f32_16x16x32_bf16 v[80:83], v[160:163], v[152:155], 0
	v_mfma_f32_16x16x32_bf16 v[84:87], v[168:171], v[152:155], 0
	v_mfma_f32_16x16x32_bf16 v[80:83], v[164:167], v[156:159], v[80:83]
	v_mfma_f32_16x16x32_bf16 v[84:87], v[172:175], v[156:159], v[84:87]
	s_waitcnt vmcnt(12)
	ds_read_b128 v[160:163], v180 offset:12288
	ds_read_b128 v[164:167], v181 offset:12288
	ds_read_b128 v[168:171], v180 offset:14336
	ds_read_b128 v[172:175], v181 offset:14336
	s_waitcnt lgkmcnt(0)
	s_mov_b32 m0, s49
	s_nop 0
	global_load_lds_dwordx4 v12, s[26:27]
	global_load_lds_dwordx4 v13, s[26:27] offset:1024
	global_load_lds_dwordx4 v14, s[26:27] offset:2048
	global_load_lds_dwordx4 v15, s[26:27] offset:3072
	v_mfma_f32_16x16x32_bf16 v[88:91], v[160:163], v[152:155], 0
	v_mfma_f32_16x16x32_bf16 v[92:95], v[168:171], v[152:155], 0
	v_mfma_f32_16x16x32_bf16 v[88:91], v[164:167], v[156:159], v[88:91]
	v_mfma_f32_16x16x32_bf16 v[92:95], v[172:175], v[156:159], v[92:95]
	s_nop 7
	s_nop 3
	s_cmp_ge_u32 s44, 0x100
	s_cbranch_scc1 .Lattn_nomask_10
	s_cmp_ge_u32 s44, 0xc0
	s_cbranch_scc1 .Lattn_m192_11
	s_cmp_ge_u32 s44, 0x80
	s_cbranch_scc1 .Lattn_m128_12
	v_mov_b32_e32 v48, 0xf149f2ca
	v_mov_b32_e32 v49, 0xf149f2ca
	v_mov_b32_e32 v50, 0xf149f2ca
	v_mov_b32_e32 v51, 0xf149f2ca
	v_mov_b32_e32 v52, 0xf149f2ca
	v_mov_b32_e32 v53, 0xf149f2ca
	v_mov_b32_e32 v54, 0xf149f2ca
	v_mov_b32_e32 v55, 0xf149f2ca
	v_mov_b32_e32 v56, 0xf149f2ca
	v_mov_b32_e32 v57, 0xf149f2ca
	v_mov_b32_e32 v58, 0xf149f2ca
	v_mov_b32_e32 v59, 0xf149f2ca
	v_mov_b32_e32 v60, 0xf149f2ca
	v_mov_b32_e32 v61, 0xf149f2ca
	v_mov_b32_e32 v62, 0xf149f2ca
	v_mov_b32_e32 v63, 0xf149f2ca

; __device__ __forceinline__ void phase_attn(KP kp, int l, unsigned char* shm) {
;     ...
;       float mx = -1e30f;
; #pragma unroll
;       for (int kb = 0; kb < 16; ++kb)
; #pragma unroll
;         for (int j = 0; j < 4; ++j) {
;           const int key = kb * 16 + kg * 4 + j;
;           lg[kb][j] = key < cnt ? lg[kb][j] : -1e30f;
;           mx = fmaxf(mx, lg[kb][j]);
;         }
;       mx = fmaxf(mx, __shfl_xor(mx, 16));
;       mx = fmaxf(mx, __shfl_xor(mx, 32));
;       float sum = 0.f;
; #pragma unroll
;       for (int kb = 0; kb < 16; ++kb)
; #pragma unroll
;         for (int j = 0; j < 4; ++j) { lg[kb][j] = __builtin_amdgcn_exp2f(lg[kb][j] - mx); sum += lg[kb][j]; }
.Lattn_nomask_10:
	v_max3_f32 v176, v32, v33, v34
	v_max3_f32 v176, v176, v35, v36
	v_max3_f32 v176, v176, v37, v38
	v_max3_f32 v176, v176, v39, v40
	v_max3_f32 v176, v176, v41, v42
	v_max3_f32 v176, v176, v43, v44
	v_max3_f32 v176, v176, v45, v46
	v_max3_f32 v176, v176, v47, v48
	v_max3_f32 v176, v176, v49, v50
	v_max3_f32 v176, v176, v51, v52
	v_max3_f32 v176, v176, v53, v54
	v_max3_f32 v176, v176, v55, v56
	v_max3_f32 v176, v176, v57, v58
	v_max3_f32 v176, v176, v59, v60
	v_max3_f32 v176, v176, v61, v62
	v_max3_f32 v176, v176, v63, v64
	v_max3_f32 v176, v176, v65, v66
	v_max3_f32 v176, v176, v67, v68
	v_max3_f32 v176, v176, v69, v70
	v_max3_f32 v176, v176, v71, v72
	v_max3_f32 v176, v176, v73, v74
	v_max3_f32 v176, v176, v75, v76
	v_max3_f32 v176, v176, v77, v78
	v_max3_f32 v176, v176, v79, v80
	v_max3_f32 v176, v176, v81, v82
	v_max3_f32 v176, v176, v83, v84
	v_max3_f32 v176, v176, v85, v86
	v_max3_f32 v176, v176, v87, v88
	v_max3_f32 v176, v176, v89, v90
	v_max3_f32 v176, v176, v91, v92
	v_max3_f32 v176, v176, v93, v94
	v_max_f32_e32 v176, v176, v95
	ds_bpermute_b32 v197, v191, v176
	s_waitcnt lgkmcnt(0)
	v_max_f32_e32 v176, v176, v197
	ds_bpermute_b32 v197, v192, v176
	s_waitcnt lgkmcnt(0)
	v_max_f32_e32 v176, v176, v197
	v_mov_b32_e32 v177, v176
	v_pk_add_f32 v[32:33], v[32:33], v[176:177] neg_lo:[0,1] neg_hi:[0,1]
	v_pk_add_f32 v[34:35], v[34:35], v[176:177] neg_lo:[0,1] neg_hi:[0,1]
	v_pk_add_f32 v[36:37], v[36:37], v[176:177] neg_lo:[0,1] neg_hi:[0,1]
	v_pk_add_f32 v[38:39], v[38:39], v[176:177] neg_lo:[0,1] neg_hi:[0,1]
	v_pk_add_f32 v[40:41], v[40:41], v[176:177] neg_lo:[0,1] neg_hi:[0,1]
	v_pk_add_f32 v[42:43], v[42:43], v[176:177] neg_lo:[0,1] neg_hi:[0,1]
	v_pk_add_f32 v[44:45], v[44:45], v[176:177] neg_lo:[0,1] neg_hi:[0,1]
	v_pk_add_f32 v[46:47], v[46:47], v[176:177] neg_lo:[0,1] neg_hi:[0,1]
	v_pk_add_f32 v[48:49], v[48:49], v[176:177] neg_lo:[0,1] neg_hi:[0,1]
	v_pk_add_f32 v[50:51], v[50:51], v[176:177] neg_lo:[0,1] neg_hi:[0,1]
	v_pk_add_f32 v[52:53], v[52:53], v[176:177] neg_lo:[0,1] neg_hi:[0,1]
	v_pk_add_f32 v[54:55], v[54:55], v[176:177] neg_lo:[0,1] neg_hi:[0,1]
	v_pk_add_f32 v[56:57], v[56:57], v[176:177] neg_lo:[0,1] neg_hi:[0,1]
	v_pk_add_f32 v[58:59], v[58:59], v[176:177] neg_lo:[0,1] neg_hi:[0,1]
	v_pk_add_f32 v[60:61], v[60:61], v[176:177] neg_lo:[0,1] neg_hi:[0,1]
	v_pk_add_f32 v[62:63], v[62:63], v[176:177] neg_lo:[0,1] neg_hi:[0,1]
	v_pk_add_f32 v[64:65], v[64:65], v[176:177] neg_lo:[0,1] neg_hi:[0,1]
	v_pk_add_f32 v[66:67], v[66:67], v[176:177] neg_lo:[0,1] neg_hi:[0,1]
	v_pk_add_f32 v[68:69], v[68:69], v[176:177] neg_lo:[0,1] neg_hi:[0,1]
	v_pk_add_f32 v[70:71], v[70:71], v[176:177] neg_lo:[0,1] neg_hi:[0,1]
	v_pk_add_f32 v[72:73], v[72:73], v[176:177] neg_lo:[0,1] neg_hi:[0,1]
	v_pk_add_f32 v[74:75], v[74:75], v[176:177] neg_lo:[0,1] neg_hi:[0,1]
	v_pk_add_f32 v[76:77], v[76:77], v[176:177] neg_lo:[0,1] neg_hi:[0,1]
	v_pk_add_f32 v[78:79], v[78:79], v[176:177] neg_lo:[0,1] neg_hi:[0,1]
	v_pk_add_f32 v[80:81], v[80:81], v[176:177] neg_lo:[0,1] neg_hi:[0,1]
	v_pk_add_f32 v[82:83], v[82:83], v[176:177] neg_lo:[0,1] neg_hi:[0,1]
	v_pk_add_f32 v[84:85], v[84:85], v[176:177] neg_lo:[0,1] neg_hi:[0,1]
	v_pk_add_f32 v[86:87], v[86:87], v[176:177] neg_lo:[0,1] neg_hi:[0,1]
	v_pk_add_f32 v[88:89], v[88:89], v[176:177] neg_lo:[0,1] neg_hi:[0,1]
	v_pk_add_f32 v[90:91], v[90:91], v[176:177] neg_lo:[0,1] neg_hi:[0,1]
	v_pk_add_f32 v[92:93], v[92:93], v[176:177] neg_lo:[0,1] neg_hi:[0,1]
	v_pk_add_f32 v[94:95], v[94:95], v[176:177] neg_lo:[0,1] neg_hi:[0,1]
	v_exp_f32_e32 v32, v32
	v_exp_f32_e32 v33, v33
	v_exp_f32_e32 v34, v34
	v_exp_f32_e32 v35, v35
	v_exp_f32_e32 v36, v36
	v_exp_f32_e32 v37, v37
	v_pk_add_f32 v[178:179], v[32:33], v[34:35]
	v_exp_f32_e32 v38, v38
	v_exp_f32_e32 v39, v39
	v_pk_add_f32 v[178:179], v[178:179], v[36:37]
	v_exp_f32_e32 v40, v40
	v_exp_f32_e32 v41, v41
	v_pk_add_f32 v[178:179], v[178:179], v[38:39]
	v_exp_f32_e32 v42, v42
	v_exp_f32_e32 v43, v43
	v_pk_add_f32 v[178:179], v[178:179], v[40:41]
	v_exp_f32_e32 v44, v44
	v_exp_f32_e32 v45, v45
	v_pk_add_f32 v[178:179], v[178:179], v[42:43]
	v_exp_f32_e32 v46, v46
	v_exp_f32_e32 v47, v47
	v_pk_add_f32 v[178:179], v[178:179], v[44:45]
	v_exp_f32_e32 v48, v48
	v_exp_f32_e32 v49, v49
	v_pk_add_f32 v[178:179], v[178:179], v[46:47]
	v_exp_f32_e32 v50, v50
	v_exp_f32_e32 v51, v51
	v_pk_add_f32 v[178:179], v[178:179], v[48:49]
	v_exp_f32_e32 v52, v52
	v_exp_f32_e32 v53, v53
	v_pk_add_f32 v[178:179], v[178:179], v[50:51]
	v_exp_f32_e32 v54, v54
	v_exp_f32_e32 v55, v55
	v_pk_add_f32 v[178:179], v[178:179], v[52:53]
	v_exp_f32_e32 v56, v56
	v_exp_f32_e32 v57, v57
	v_pk_add_f32 v[178:179], v[178:179], v[54:55]
	v_exp_f32_e32 v58, v58
	v_exp_f32_e32 v59, v59
	v_pk_add_f32 v[178:179], v[178:179], v[56:57]
	v_exp_f32_e32 v60, v60
	v_exp_f32_e32 v61, v61
	v_pk_add_f32 v[178:179], v[178:179], v[58:59]
	v_exp_f32_e32 v62, v62
	v_exp_f32_e32 v63, v63
	v_pk_add_f32 v[178:179], v[178:179], v[60:61]
	v_exp_f32_e32 v64, v64
	v_exp_f32_e32 v65, v65
	v_pk_add_f32 v[178:179], v[178:179], v[62:63]
	v_exp_f32_e32 v66, v66
	v_exp_f32_e32 v67, v67
	v_pk_add_f32 v[178:179], v[178:179], v[64:65]
	v_exp_f32_e32 v68, v68
	v_exp_f32_e32 v69, v69
	v_pk_add_f32 v[178:179], v[178:179], v[66:67]
	v_exp_f32_e32 v70, v70
	v_exp_f32_e32 v71, v71
	v_pk_add_f32 v[178:179], v[178:179], v[68:69]
	v_exp_f32_e32 v72, v72
	v_exp_f32_e32 v73, v73
	v_pk_add_f32 v[178:179], v[178:179], v[70:71]
	v_exp_f32_e32 v74, v74
	v_exp_f32_e32 v75, v75
	v_pk_add_f32 v[178:179], v[178:179], v[72:73]
	v_exp_f32_e32 v76, v76
	v_exp_f32_e32 v77, v77
	v_pk_add_f32 v[178:179], v[178:179], v[74:75]
; __device__ __forceinline__ void phase_attn(KP kp, int l, unsigned char* shm) {
;     ...
;       float sum = 0.f;
; #pragma unroll
;       for (int kb = 0; kb < 16; ++kb)
; #pragma unroll
;         for (int j = 0; j < 4; ++j) { lg[kb][j] = __builtin_amdgcn_exp2f(lg[kb][j] - mx); sum += lg[kb][j]; }
;       sum += __shfl_xor(sum, 16);
;       sum += __shfl_xor(sum, 32);
;       const float inv = 1.f / sum;
;       bf16x8 pf[8];
; #pragma unroll
;       for (int s8 = 0; s8 < 8; ++s8) {
;         u32x4 pk;
;         pk[0] = cvt_pk_bf16(lg[2 * s8][0], lg[2 * s8][1]);
;         pk[1] = cvt_pk_bf16(lg[2 * s8][2], lg[2 * s8][3]);
;         pk[2] = cvt_pk_bf16(lg[2 * s8 + 1][0], lg[2 * s8 + 1][1]);
;         pk[3] = cvt_pk_bf16(lg[2 * s8 + 1][2], lg[2 * s8 + 1][3]);
;         pf[s8] = __builtin_bit_cast(bf16x8, pk);
;       }
;       f32x4 oacc[4];
; #pragma unroll
;       for (int c = 0; c < 4; ++c) oacc[c] = (f32x4){0.f, 0.f, 0.f, 0.f};
;       for (int repV = 0; repV < ((PROBE & 256) ? 2 : 1); ++repV)
;       {
;         if (repV) {
; #pragma unroll
;           for (int c = 0; c < 4; ++c) oacc[c] = (f32x4){0.f, 0.f, 0.f, 0.f};
;         }
; #pragma unroll
;         for (int i = 16; i < 32; ++i) {
;           const int idx = selw[i * 8 + ks8];
;           vr[i] = *(const u32x4*)(vbase + (size_t)idx * 128 + kvh * 64 + dc * 8);
;         }
; #pragma unroll
;         for (int s8 = 0; s8 < 8; ++s8) {
; #pragma unroll
;           for (int it = 0; it < 4; ++it) *(u32x4*)(tileb + (it * 8 + ks8) * 144 + dc * 16) = vr[s8 * 4 + it];
;           u32x2 t0, t1, t2, t3, t4, t5, t6, t7;
;           asm volatile(
;               "ds_read_b64_tr_b16 %0, %8\n\tds_read_b64_tr_b16 %1, %8 offset:2304\n\t"
;               "ds_read_b64_tr_b16 %2, %8 offset:32\n\tds_read_b64_tr_b16 %3, %8 offset:2336\n\t"
;               "ds_read_b64_tr_b16 %4, %8 offset:64\n\tds_read_b64_tr_b16 %5, %8 offset:2368\n\t"
;               "ds_read_b64_tr_b16 %6, %8 offset:96\n\tds_read_b64_tr_b16 %7, %8 offset:2400\n\t"
;               "s_waitcnt lgkmcnt(0)"
;               : "=&v"(t0), "=&v"(t1), "=&v"(t2), "=&v"(t3), "=&v"(t4), "=&v"(t5), "=&v"(t6), "=&v"(t7)
;               : "v"(tr_addr)
;               : "memory");
;           const bf16x8 a0 = __builtin_bit_cast(bf16x8, (u32x4){t0[0], t0[1], t1[0], t1[1]});
;           const bf16x8 a1 = __builtin_bit_cast(bf16x8, (u32x4){t2[0], t2[1], t3[0], t3[1]});
	v_exp_f32_e32 v78, v78
	v_exp_f32_e32 v79, v79
	v_pk_add_f32 v[178:179], v[178:179], v[76:77]
	v_exp_f32_e32 v80, v80
	v_exp_f32_e32 v81, v81
	v_pk_add_f32 v[178:179], v[178:179], v[78:79]
	v_exp_f32_e32 v82, v82
	v_exp_f32_e32 v83, v83
	v_pk_add_f32 v[178:179], v[178:179], v[80:81]
	v_exp_f32_e32 v84, v84
	v_exp_f32_e32 v85, v85
	v_pk_add_f32 v[178:179], v[178:179], v[82:83]
	v_exp_f32_e32 v86, v86
	v_exp_f32_e32 v87, v87
	v_pk_add_f32 v[178:179], v[178:179], v[84:85]
	v_exp_f32_e32 v88, v88
	v_exp_f32_e32 v89, v89
	v_pk_add_f32 v[178:179], v[178:179], v[86:87]
	v_exp_f32_e32 v90, v90
	v_exp_f32_e32 v91, v91
	v_pk_add_f32 v[178:179], v[178:179], v[88:89]
	v_exp_f32_e32 v92, v92
	v_exp_f32_e32 v93, v93
	v_pk_add_f32 v[178:179], v[178:179], v[90:91]
	v_exp_f32_e32 v94, v94
	v_exp_f32_e32 v95, v95
	v_pk_add_f32 v[178:179], v[178:179], v[92:93]
	s_nop 0
	v_pk_add_f32 v[178:179], v[178:179], v[94:95]
	v_add_f32_e32 v210, v178, v179
	ds_bpermute_b32 v197, v191, v210
	v_cvt_pk_bf16_f32 v96, v32, v33
	v_cvt_pk_bf16_f32 v97, v34, v35
	v_cvt_pk_bf16_f32 v98, v36, v37
	v_cvt_pk_bf16_f32 v99, v38, v39
	v_cvt_pk_bf16_f32 v100, v40, v41
	v_cvt_pk_bf16_f32 v101, v42, v43
	v_cvt_pk_bf16_f32 v102, v44, v45
	v_cvt_pk_bf16_f32 v103, v46, v47
	v_cvt_pk_bf16_f32 v104, v48, v49
	v_cvt_pk_bf16_f32 v105, v50, v51
	v_cvt_pk_bf16_f32 v106, v52, v53
	v_cvt_pk_bf16_f32 v107, v54, v55
	v_cvt_pk_bf16_f32 v108, v56, v57
	v_cvt_pk_bf16_f32 v109, v58, v59
	v_cvt_pk_bf16_f32 v110, v60, v61
	v_cvt_pk_bf16_f32 v111, v62, v63
	s_waitcnt lgkmcnt(0)
	v_add_f32_e32 v210, v210, v197
	ds_bpermute_b32 v197, v192, v210
	v_cvt_pk_bf16_f32 v112, v64, v65
	v_cvt_pk_bf16_f32 v113, v66, v67
	v_cvt_pk_bf16_f32 v114, v68, v69
	v_cvt_pk_bf16_f32 v115, v70, v71
	v_cvt_pk_bf16_f32 v116, v72, v73
	v_cvt_pk_bf16_f32 v117, v74, v75
	v_cvt_pk_bf16_f32 v118, v76, v77
	v_cvt_pk_bf16_f32 v119, v78, v79
	v_cvt_pk_bf16_f32 v120, v80, v81
	v_cvt_pk_bf16_f32 v121, v82, v83
	v_cvt_pk_bf16_f32 v122, v84, v85
	v_cvt_pk_bf16_f32 v123, v86, v87
	v_cvt_pk_bf16_f32 v124, v88, v89
	v_cvt_pk_bf16_f32 v125, v90, v91
	v_cvt_pk_bf16_f32 v126, v92, v93
	v_cvt_pk_bf16_f32 v127, v94, v95
	s_waitcnt lgkmcnt(0)
	v_add_f32_e32 v210, v210, v197
	v_rcp_f32_e32 v208, v210
	s_waitcnt vmcnt(12)
	ds_read_b64_tr_b16 v[160:161], v182 offset:0
	ds_read_b64_tr_b16 v[162:163], v182 offset:2048
	ds_read_b64_tr_b16 v[164:165], v183 offset:0
	ds_read_b64_tr_b16 v[166:167], v183 offset:2048
	ds_read_b64_tr_b16 v[168:169], v184 offset:0
	ds_read_b64_tr_b16 v[170:171], v184 offset:2048
	ds_read_b64_tr_b16 v[172:173], v185 offset:0
	ds_read_b64_tr_b16 v[174:175], v185 offset:2048
	s_mov_b64 exec, s[42:43]
	global_load_dwordx4 v[144:147], v189, s[40:41]
	global_load_dwordx4 v[148:151], v189, s[40:41] offset:64
	global_load_dwordx4 v[152:155], v189, s[40:41] offset:512
	global_load_dwordx4 v[156:159], v189, s[40:41] offset:576
	s_mov_b64 exec, -1
	s_waitcnt lgkmcnt(0)
	s_mov_b32 m0, s46
	s_nop 0
	global_load_lds_dwordx4 v16, s[26:27]
	global_load_lds_dwordx4 v18, s[26:27] offset:1024
	global_load_lds_dwordx4 v19, s[26:27] offset:2048
	global_load_lds_dwordx4 v20, s[26:27] offset:3072
	v_mfma_f32_16x16x32_bf16 v[128:131], v[160:163], v[96:99], 0
	v_mfma_f32_16x16x32_bf16 v[132:135], v[164:167], v[96:99], 0
	v_mfma_f32_16x16x32_bf16 v[136:139], v[168:171], v[96:99], 0
	v_mfma_f32_16x16x32_bf16 v[140:143], v[172:175], v[96:99], 0
	s_waitcnt vmcnt(16)
	ds_read_b64_tr_b16 v[160:161], v182 offset:4096
	ds_read_b64_tr_b16 v[162:163], v182 offset:6144
	ds_read_b64_tr_b16 v[164:165], v183 offset:4096
	ds_read_b64_tr_b16 v[166:167], v183 offset:6144
	ds_read_b64_tr_b16 v[168:169], v184 offset:4096
	ds_read_b64_tr_b16 v[170:171], v184 offset:6144
	ds_read_b64_tr_b16 v[172:173], v185 offset:4096
	ds_read_b64_tr_b16 v[174:175], v185 offset:6144
	s_waitcnt lgkmcnt(0)
	s_mov_b32 m0, s47
	s_nop 0
	global_load_lds_dwordx4 v21, s[26:27]
	global_load_lds_dwordx4 v22, s[26:27] offset:1024
	global_load_lds_dwordx4 v23, s[26:27] offset:2048
	global_load_lds_dwordx4 v24, s[26:27] offset:3072
	v_mfma_f32_16x16x32_bf16 v[128:131], v[160:163], v[100:103], v[128:131]
	v_mfma_f32_16x16x32_bf16 v[132:135], v[164:167], v[100:103], v[132:135]
	v_mfma_f32_16x16x32_bf16 v[136:139], v[168:171], v[100:103], v[136:139]
	v_mfma_f32_16x16x32_bf16 v[140:143], v[172:175], v[100:103], v[140:143]
	s_waitcnt vmcnt(16)
	ds_read_b64_tr_b16 v[160:161], v182 offset:8192
	ds_read_b64_tr_b16 v[162:163], v182 offset:10240
	ds_read_b64_tr_b16 v[164:165], v183 offset:8192
	ds_read_b64_tr_b16 v[166:167], v183 offset:10240
	ds_read_b64_tr_b16 v[168:169], v184 offset:8192
	ds_read_b64_tr_b16 v[170:171], v184 offset:10240
	ds_read_b64_tr_b16 v[172:173], v185 offset:8192
	ds_read_b64_tr_b16 v[174:175], v185 offset:10240
	s_waitcnt lgkmcnt(0)
	s_mov_b32 m0, s48
	s_nop 0
	global_load_lds_dwordx4 v25, s[26:27]
	global_load_lds_dwordx4 v26, s[26:27] offset:1024
	global_load_lds_dwordx4 v27, s[26:27] offset:2048
	global_load_lds_dwordx4 v28, s[26:27] offset:3072
	v_mfma_f32_16x16x32_bf16 v[128:131], v[160:163], v[104:107], v[128:131]
	v_mfma_f32_16x16x32_bf16 v[132:135], v[164:167], v[104:107], v[132:135]
	v_mfma_f32_16x16x32_bf16 v[136:139], v[168:171], v[104:107], v[136:139]
	v_mfma_f32_16x16x32_bf16 v[140:143], v[172:175], v[104:107], v[140:143]
	s_waitcnt vmcnt(16)
	ds_read_b64_tr_b16 v[160:161], v182 offset:12288
	ds_read_b64_tr_b16 v[162:163], v182 offset:14336
	ds_read_b64_tr_b16 v[164:165], v183 offset:12288
	ds_read_b64_tr_b16 v[166:167], v183 offset:14336
	ds_read_b64_tr_b16 v[168:169], v184 offset:12288
	ds_read_b64_tr_b16 v[170:171], v184 offset:14336
	ds_read_b64_tr_b16 v[172:173], v185 offset:12288
	ds_read_b64_tr_b16 v[174:175], v185 offset:14336
	s_waitcnt lgkmcnt(0)
; __device__ __forceinline__ void phase_attn(KP kp, int l, unsigned char* shm) {
;     ...
;     const int cnt = n < 256 ? n : 256;
;     {
;       u32x2 sv = *(const u32x2*)(SEL + (size_t)r * 256 + lane * 4);
;       const int k0 = lane * 4;
;       unsigned a0 = sv[0] & 0xffffu, a1 = sv[0] >> 16, a2 = sv[1] & 0xffffu, a3 = sv[1] >> 16;
;       a0 = (k0 < cnt) ? a0 : 0u; a1 = (k0 + 1 < cnt) ? a1 : 0u; a2 = (k0 + 2 < cnt) ? a2 : 0u; a3 = (k0 + 3 < cnt) ? a3 : 0u;
;       u32x2 o;
;       o[0] = a0 | (a1 << 16); o[1] = a2 | (a3 << 16);
;       *(u32x2*)(selw + lane * 4) = o;
;     }
;     ...
;         for (int i = 16; i < 32; ++i) {
;           const int idx = selw[i * 8 + ks8];
;           vr[i] = *(const u32x4*)(vbase + (size_t)idx * 128 + kvh * 64 + dc * 8);
;         }
; #pragma unroll
;         for (int s8 = 0; s8 < 8; ++s8) {
; #pragma unroll
;           for (int it = 0; it < 4; ++it) *(u32x4*)(tileb + (it * 8 + ks8) * 144 + dc * 16) = vr[s8 * 4 + it];
;           u32x2 t0, t1, t2, t3, t4, t5, t6, t7;
;           asm volatile(
;               "ds_read_b64_tr_b16 %0, %8\n\tds_read_b64_tr_b16 %1, %8 offset:2304\n\t"
;               "ds_read_b64_tr_b16 %2, %8 offset:32\n\tds_read_b64_tr_b16 %3, %8 offset:2336\n\t"
;               "ds_read_b64_tr_b16 %4, %8 offset:64\n\tds_read_b64_tr_b16 %5, %8 offset:2368\n\t"
;               "ds_read_b64_tr_b16 %6, %8 offset:96\n\tds_read_b64_tr_b16 %7, %8 offset:2400\n\t"
;               "s_waitcnt lgkmcnt(0)"
;               : "=&v"(t0), "=&v"(t1), "=&v"(t2), "=&v"(t3), "=&v"(t4), "=&v"(t5), "=&v"(t6), "=&v"(t7)
;               : "v"(tr_addr)
;               : "memory");
;           const bf16x8 a0 = __builtin_bit_cast(bf16x8, (u32x4){t0[0], t0[1], t1[0], t1[1]});
;           const bf16x8 a1 = __builtin_bit_cast(bf16x8, (u32x4){t2[0], t2[1], t3[0], t3[1]});
;           const bf16x8 a2 = __builtin_bit_cast(bf16x8, (u32x4){t4[0], t4[1], t5[0], t5[1]});
;           const bf16x8 a3 = __builtin_bit_cast(bf16x8, (u32x4){t6[0], t6[1], t7[0], t7[1]});
;           oacc[0] = __builtin_amdgcn_mfma_f32_16x16x32_bf16(a0, pf[s8], oacc[0], 0, 0, 0);
;           oacc[1] = __builtin_amdgcn_mfma_f32_16x16x32_bf16(a1, pf[s8], oacc[1], 0, 0, 0);
;           oacc[2] = __builtin_amdgcn_mfma_f32_16x16x32_bf16(a2, pf[s8], oacc[2], 0, 0, 0);
;           oacc[3] = __builtin_amdgcn_mfma_f32_16x16x32_bf16(a3, pf[s8], oacc[3], 0, 0, 0);
	s_mov_b32 m0, s49
	s_nop 0
	global_load_lds_dwordx4 v29, s[26:27]
	global_load_lds_dwordx4 v30, s[26:27] offset:1024
	global_load_lds_dwordx4 v31, s[26:27] offset:2048
	global_load_lds_dwordx4 v219, s[26:27] offset:3072
	v_mfma_f32_16x16x32_bf16 v[128:131], v[160:163], v[108:111], v[128:131]
	v_mfma_f32_16x16x32_bf16 v[132:135], v[164:167], v[108:111], v[132:135]
	v_mfma_f32_16x16x32_bf16 v[136:139], v[168:171], v[108:111], v[136:139]
	v_mfma_f32_16x16x32_bf16 v[140:143], v[172:175], v[108:111], v[140:143]
	s_lshr_b32 s6, s45, 2
	v_cmp_gt_u32_e32 vcc, s6, v252
	s_nop 1
	v_cndmask_b32_e32 v198, 0, v198, vcc
	v_cndmask_b32_e32 v199, 0, v199, vcc
	ds_write_b64 v186, v[198:199]
	ds_read_u16 v0, v187 offset:0
	ds_read_u16 v1, v187 offset:16
	ds_read_u16 v2, v187 offset:32
	ds_read_u16 v3, v187 offset:48
	ds_read_u16 v4, v187 offset:64
	ds_read_u16 v5, v187 offset:80
	ds_read_u16 v6, v187 offset:96
	ds_read_u16 v7, v187 offset:112
	s_waitcnt lgkmcnt(0)
	v_lshl_add_u32 v0, v0, 8, v193
	v_lshl_add_u32 v1, v1, 8, v194
	v_lshl_add_u32 v2, v2, 8, v195
	v_lshl_add_u32 v3, v3, 8, v196
	v_lshl_add_u32 v4, v4, 8, v193
	v_lshl_add_u32 v5, v5, 8, v194
	v_lshl_add_u32 v6, v6, 8, v195
	v_lshl_add_u32 v7, v7, 8, v196
	ds_read_u16 v8, v187 offset:128
	ds_read_u16 v9, v187 offset:144
	ds_read_u16 v10, v187 offset:160
	ds_read_u16 v11, v187 offset:176
	ds_read_u16 v12, v187 offset:192
	ds_read_u16 v13, v187 offset:208
	ds_read_u16 v14, v187 offset:224
	ds_read_u16 v15, v187 offset:240
	s_waitcnt lgkmcnt(0)
	v_lshl_add_u32 v8, v8, 8, v193
	v_lshl_add_u32 v9, v9, 8, v194
	v_lshl_add_u32 v10, v10, 8, v195
	v_lshl_add_u32 v11, v11, 8, v196
	v_lshl_add_u32 v12, v12, 8, v193
	v_lshl_add_u32 v13, v13, 8, v194
	v_lshl_add_u32 v14, v14, 8, v195
	v_lshl_add_u32 v15, v15, 8, v196
	ds_read_u16 v16, v187 offset:256
	ds_read_u16 v18, v187 offset:272
	ds_read_u16 v19, v187 offset:288
	ds_read_u16 v20, v187 offset:304
	ds_read_u16 v21, v187 offset:320
	ds_read_u16 v22, v187 offset:336
	ds_read_u16 v23, v187 offset:352
	ds_read_u16 v24, v187 offset:368
	s_waitcnt lgkmcnt(0)
	v_lshl_add_u32 v16, v16, 8, v193
	v_lshl_add_u32 v18, v18, 8, v194
	v_lshl_add_u32 v19, v19, 8, v195
	v_lshl_add_u32 v20, v20, 8, v196
	v_lshl_add_u32 v21, v21, 8, v193
	v_lshl_add_u32 v22, v22, 8, v194
	v_lshl_add_u32 v23, v23, 8, v195
	v_lshl_add_u32 v24, v24, 8, v196
	ds_read_u16 v25, v187 offset:384
	ds_read_u16 v26, v187 offset:400
	ds_read_u16 v27, v187 offset:416
	ds_read_u16 v28, v187 offset:432
	ds_read_u16 v29, v187 offset:448
	ds_read_u16 v30, v187 offset:464
	ds_read_u16 v31, v187 offset:480
	ds_read_u16 v219, v187 offset:496
	s_waitcnt lgkmcnt(0)
	v_lshl_add_u32 v25, v25, 8, v193
	v_lshl_add_u32 v26, v26, 8, v194
	v_lshl_add_u32 v27, v27, 8, v195
	v_lshl_add_u32 v28, v28, 8, v196
	v_lshl_add_u32 v29, v29, 8, v193
	v_lshl_add_u32 v30, v30, 8, v194
	v_lshl_add_u32 v31, v31, 8, v195
	v_lshl_add_u32 v219, v219, 8, v196
	s_waitcnt vmcnt(12)
	ds_read_b64_tr_b16 v[160:161], v182 offset:0
	ds_read_b64_tr_b16 v[162:163], v182 offset:2048
	ds_read_b64_tr_b16 v[164:165], v183 offset:0
	ds_read_b64_tr_b16 v[166:167], v183 offset:2048
	ds_read_b64_tr_b16 v[168:169], v184 offset:0
	ds_read_b64_tr_b16 v[170:171], v184 offset:2048
	ds_read_b64_tr_b16 v[172:173], v185 offset:0
	ds_read_b64_tr_b16 v[174:175], v185 offset:2048
	s_waitcnt lgkmcnt(0)
	s_mov_b32 m0, s46
	s_nop 0
	global_load_lds_dwordx4 v0, s[28:29]
	global_load_lds_dwordx4 v1, s[28:29] offset:1024
	global_load_lds_dwordx4 v2, s[28:29] offset:2048
	global_load_lds_dwordx4 v3, s[28:29] offset:3072
	v_mfma_f32_16x16x32_bf16 v[128:131], v[160:163], v[112:115], v[128:131]
	v_mfma_f32_16x16x32_bf16 v[132:135], v[164:167], v[112:115], v[132:135]
	v_mfma_f32_16x16x32_bf16 v[136:139], v[168:171], v[112:115], v[136:139]
	v_mfma_f32_16x16x32_bf16 v[140:143], v[172:175], v[112:115], v[140:143]
	s_waitcnt vmcnt(12)
; __device__ __forceinline__ void phase_attn(KP kp, int l, unsigned char* shm) {
;     ...
;         for (int i = 16; i < 32; ++i) {
;           const int idx = selw[i * 8 + ks8];
;           vr[i] = *(const u32x4*)(vbase + (size_t)idx * 128 + kvh * 64 + dc * 8);
;         }
; #pragma unroll
;         for (int s8 = 0; s8 < 8; ++s8) {
; #pragma unroll
;           for (int it = 0; it < 4; ++it) *(u32x4*)(tileb + (it * 8 + ks8) * 144 + dc * 16) = vr[s8 * 4 + it];
;           u32x2 t0, t1, t2, t3, t4, t5, t6, t7;
;           asm volatile(
;               "ds_read_b64_tr_b16 %0, %8\n\tds_read_b64_tr_b16 %1, %8 offset:2304\n\t"
;               "ds_read_b64_tr_b16 %2, %8 offset:32\n\tds_read_b64_tr_b16 %3, %8 offset:2336\n\t"
;               "ds_read_b64_tr_b16 %4, %8 offset:64\n\tds_read_b64_tr_b16 %5, %8 offset:2368\n\t"
;               "ds_read_b64_tr_b16 %6, %8 offset:96\n\tds_read_b64_tr_b16 %7, %8 offset:2400\n\t"
;               "s_waitcnt lgkmcnt(0)"
;               : "=&v"(t0), "=&v"(t1), "=&v"(t2), "=&v"(t3), "=&v"(t4), "=&v"(t5), "=&v"(t6), "=&v"(t7)
;               : "v"(tr_addr)
;               : "memory");
;           const bf16x8 a0 = __builtin_bit_cast(bf16x8, (u32x4){t0[0], t0[1], t1[0], t1[1]});
;           const bf16x8 a1 = __builtin_bit_cast(bf16x8, (u32x4){t2[0], t2[1], t3[0], t3[1]});
;           const bf16x8 a2 = __builtin_bit_cast(bf16x8, (u32x4){t4[0], t4[1], t5[0], t5[1]});
;           const bf16x8 a3 = __builtin_bit_cast(bf16x8, (u32x4){t6[0], t6[1], t7[0], t7[1]});
;           oacc[0] = __builtin_amdgcn_mfma_f32_16x16x32_bf16(a0, pf[s8], oacc[0], 0, 0, 0);
;           oacc[1] = __builtin_amdgcn_mfma_f32_16x16x32_bf16(a1, pf[s8], oacc[1], 0, 0, 0);
;           oacc[2] = __builtin_amdgcn_mfma_f32_16x16x32_bf16(a2, pf[s8], oacc[2], 0, 0, 0);
;           oacc[3] = __builtin_amdgcn_mfma_f32_16x16x32_bf16(a3, pf[s8], oacc[3], 0, 0, 0);
;           if (kvh == 0 && s8 == 3) {
; #pragma unroll
;             for (int k8 = 0; k8 < 8; ++k8) {
;               const int idx = selw[k8 * 16 + nn];
;               const bf16_t* kp = kbase + (size_t)idx * 128 + 64 + kg * 8;
;               kpre[k8][0] = *(const bf16x8*)kp;
;               kpre[k8][1] = *(const bf16x8*)(kp + 32);
;             }
;           }
;         }
;         __builtin_amdgcn_sched_barrier(0);
;       }
;       if (nn < 4) {
; #pragma unroll
;         for (int c = 0; c < 4; ++c) {
	ds_read_b64_tr_b16 v[160:161], v182 offset:4096
	ds_read_b64_tr_b16 v[162:163], v182 offset:6144
	ds_read_b64_tr_b16 v[164:165], v183 offset:4096
	ds_read_b64_tr_b16 v[166:167], v183 offset:6144
	ds_read_b64_tr_b16 v[168:169], v184 offset:4096
	ds_read_b64_tr_b16 v[170:171], v184 offset:6144
	ds_read_b64_tr_b16 v[172:173], v185 offset:4096
	ds_read_b64_tr_b16 v[174:175], v185 offset:6144
	s_waitcnt lgkmcnt(0)
	s_mov_b32 m0, s47
	s_nop 0
	global_load_lds_dwordx4 v4, s[28:29]
	global_load_lds_dwordx4 v5, s[28:29] offset:1024
	global_load_lds_dwordx4 v6, s[28:29] offset:2048
	global_load_lds_dwordx4 v7, s[28:29] offset:3072
	v_mfma_f32_16x16x32_bf16 v[128:131], v[160:163], v[116:119], v[128:131]
	v_mfma_f32_16x16x32_bf16 v[132:135], v[164:167], v[116:119], v[132:135]
	v_mfma_f32_16x16x32_bf16 v[136:139], v[168:171], v[116:119], v[136:139]
	v_mfma_f32_16x16x32_bf16 v[140:143], v[172:175], v[116:119], v[140:143]
	s_waitcnt vmcnt(12)
	ds_read_b64_tr_b16 v[160:161], v182 offset:8192
	ds_read_b64_tr_b16 v[162:163], v182 offset:10240
	ds_read_b64_tr_b16 v[164:165], v183 offset:8192
	ds_read_b64_tr_b16 v[166:167], v183 offset:10240
	ds_read_b64_tr_b16 v[168:169], v184 offset:8192
	ds_read_b64_tr_b16 v[170:171], v184 offset:10240
	ds_read_b64_tr_b16 v[172:173], v185 offset:8192
	ds_read_b64_tr_b16 v[174:175], v185 offset:10240
	s_waitcnt lgkmcnt(0)
	s_mov_b32 m0, s48
	s_nop 0
	global_load_lds_dwordx4 v8, s[28:29]
	global_load_lds_dwordx4 v9, s[28:29] offset:1024
	global_load_lds_dwordx4 v10, s[28:29] offset:2048
	global_load_lds_dwordx4 v11, s[28:29] offset:3072
	v_mfma_f32_16x16x32_bf16 v[128:131], v[160:163], v[120:123], v[128:131]
	v_mfma_f32_16x16x32_bf16 v[132:135], v[164:167], v[120:123], v[132:135]
	v_mfma_f32_16x16x32_bf16 v[136:139], v[168:171], v[120:123], v[136:139]
	v_mfma_f32_16x16x32_bf16 v[140:143], v[172:175], v[120:123], v[140:143]
	s_waitcnt vmcnt(12)
	ds_read_b64_tr_b16 v[160:161], v182 offset:12288
	ds_read_b64_tr_b16 v[162:163], v182 offset:14336
	ds_read_b64_tr_b16 v[164:165], v183 offset:12288
	ds_read_b64_tr_b16 v[166:167], v183 offset:14336
	ds_read_b64_tr_b16 v[168:169], v184 offset:12288
	ds_read_b64_tr_b16 v[170:171], v184 offset:14336
	ds_read_b64_tr_b16 v[172:173], v185 offset:12288
	ds_read_b64_tr_b16 v[174:175], v185 offset:14336
	s_waitcnt lgkmcnt(0)
	s_mov_b32 m0, s49
	s_nop 0
	global_load_lds_dwordx4 v12, s[28:29]
	global_load_lds_dwordx4 v13, s[28:29] offset:1024
	global_load_lds_dwordx4 v14, s[28:29] offset:2048
	global_load_lds_dwordx4 v15, s[28:29] offset:3072
	v_mfma_f32_16x16x32_bf16 v[128:131], v[160:163], v[124:127], v[128:131]
	v_mfma_f32_16x16x32_bf16 v[132:135], v[164:167], v[124:127], v[132:135]
	v_mfma_f32_16x16x32_bf16 v[136:139], v[168:171], v[124:127], v[136:139]
	v_mfma_f32_16x16x32_bf16 v[140:143], v[172:175], v[124:127], v[140:143]
	s_nop 7
	s_nop 3
	v_mul_f32_e32 v128, v208, v128
	v_mul_f32_e32 v129, v208, v129
	v_mul_f32_e32 v130, v208, v130
	v_mul_f32_e32 v131, v208, v131
	v_cvt_pk_bf16_f32 v200, v128, v129
	v_cvt_pk_bf16_f32 v201, v130, v131
	v_mul_f32_e32 v132, v208, v132
	v_mul_f32_e32 v133, v208, v133
	v_mul_f32_e32 v134, v208, v134
	v_mul_f32_e32 v135, v208, v135
	v_cvt_pk_bf16_f32 v202, v132, v133
	v_cvt_pk_bf16_f32 v203, v134, v135
	v_mul_f32_e32 v136, v208, v136
	v_mul_f32_e32 v137, v208, v137
	v_mul_f32_e32 v138, v208, v138
	v_mul_f32_e32 v139, v208, v139
	v_cvt_pk_bf16_f32 v204, v136, v137
	v_cvt_pk_bf16_f32 v205, v138, v139
	v_mul_f32_e32 v140, v208, v140
	v_mul_f32_e32 v141, v208, v141
	v_mul_f32_e32 v142, v208, v142
	v_mul_f32_e32 v143, v208, v143
	v_cvt_pk_bf16_f32 v206, v140, v141
	v_cvt_pk_bf16_f32 v207, v142, v143
	s_mov_b64 exec, s[42:43]
	global_store_dwordx2 v190, v[200:201], s[34:35] offset:512
	global_store_dwordx2 v190, v[202:203], s[34:35] offset:544
	global_store_dwordx2 v190, v[204:205], s[34:35] offset:576
	global_store_dwordx2 v190, v[206:207], s[34:35] offset:608
	s_mov_b64 exec, -1
	s_mov_b64 s[20:21], s[28:29]
	s_mov_b64 s[22:23], s[30:31]
	s_add_u32 s24, s28, 0x80
	s_addc_u32 s25, s29, 0
	s_add_u32 s26, s30, 0x80
	s_addc_u32 s27, s31, 0
	s_mov_b64 s[34:35], s[36:37]
	s_mov_b32 s44, s45
	s_mov_b32 s2, s50
	s_cmp_lt_i32 s2, 0x8200
	s_cbranch_scc1 .Lattn_loop
